# I + ACT stored tile-major ([panel][k-tile][row][128B]) by the SwiGLU epilogue and read that way by FFN-out's A operand (separate per-lane A offsets)
# speedup vs baseline: 1.0066x; 1.0066x over previous
; __device__ __forceinline__ unsigned cvt_pk_bf16(float lo, float hi) { const pk_f2_t v = {lo, hi}; return __builtin_bit_cast(unsigned, __builtin_convertvector(v, pk_bf2_t)); }
; __device__ __forceinline__ float silu_f(float g) { return g * __builtin_amdgcn_rcpf(1.0f + __builtin_amdgcn_exp2f(-1.4426950408889634f * g)); }
;     __device__ __forceinline__ void operator()(const pg8::f32x4 (&acc)[2][2][4][2], const pg8::Unit& u, int wr, int wc, int fr, int fq) const {
;         const int row0 = u.pm * 256 + wr * 64 + fr, col0 = u.pn * 128 + wc * 32 + 8 * fq;
;         bf16* base = O + (size_t)row0 * FF + col0;
; #pragma unroll
;         for (int ai = 0; ai < 2; ++ai)
; #pragma unroll
;             for (int m = 0; m < 4; ++m) {
;                 pg8::u32x4 w;
;                 { const pg8::f32x4 g = acc[ai][0][m][0], uu = acc[ai][1][m][0];
;                   w.x = pg8::cvt_pk_bf16(silu_f(g[0]) * uu[0], silu_f(g[1]) * uu[1]); w.y = pg8::cvt_pk_bf16(silu_f(g[2]) * uu[2], silu_f(g[3]) * uu[3]); }
;                 { const pg8::f32x4 g = acc[ai][0][m][1], uu = acc[ai][1][m][1];
;                   w.z = pg8::cvt_pk_bf16(silu_f(g[0]) * uu[0], silu_f(g[1]) * uu[1]); w.w = pg8::cvt_pk_bf16(silu_f(g[2]) * uu[2], silu_f(g[3]) * uu[3]); }
;                 *(pg8::u32x4*)(base + (size_t)(ai * 128 + m * 16) * FF) = w;
.LBB0_282:
	s_lshl_b32 s100, s26, 1
	v_lshrrev_b32_e32 v141, 6, v144
	v_add_u32_e32 v141, s100, v141
	v_lshlrev_b32_e32 v141, 15, v141
	v_and_b32_e32 v140, 63, v144
	v_lshlrev_b32_e32 v140, 1, v140
	v_lshl_add_u32 v140, v142, 7, v140
	v_add_u32_e32 v140, v140, v141
	s_mul_i32 s100, s27, 0x2c0000
	s_add_u32 s100, s6, s100
	s_addc_u32 s101, s7, 0
	v_mov_b32_e32 v141, 0
	v_lshl_add_u64 v[140:141], s[100:101], 0, v[140:141]
	s_mov_b64 s[18:19], -1
	v_mul_f32_e32 v150, 0xbfb8aa3b, v126
	v_mul_f32_e32 v151, 0xbfb8aa3b, v127
	v_mul_f32_e32 v152, 0xbfb8aa3b, v128
	v_mul_f32_e32 v153, 0xbfb8aa3b, v129
	v_mul_f32_e32 v154, 0xbfb8aa3b, v118
	v_mul_f32_e32 v155, 0xbfb8aa3b, v119
	v_mul_f32_e32 v156, 0xbfb8aa3b, v120
	v_mul_f32_e32 v157, 0xbfb8aa3b, v121
	v_exp_f32_e32 v150, v150
	v_exp_f32_e32 v151, v151
	v_exp_f32_e32 v152, v152
	v_exp_f32_e32 v153, v153
	v_exp_f32_e32 v154, v154
	v_exp_f32_e32 v155, v155
	v_exp_f32_e32 v156, v156
	v_exp_f32_e32 v157, v157
	v_add_f32_e32 v150, 1.0, v150
	v_add_f32_e32 v151, 1.0, v151
	v_add_f32_e32 v152, 1.0, v152
	v_add_f32_e32 v153, 1.0, v153
	v_add_f32_e32 v154, 1.0, v154
	v_add_f32_e32 v155, 1.0, v155
	v_add_f32_e32 v156, 1.0, v156
	v_add_f32_e32 v157, 1.0, v157
	v_rcp_f32_e32 v150, v150
	v_rcp_f32_e32 v151, v151
	v_rcp_f32_e32 v152, v152
	v_rcp_f32_e32 v153, v153
	v_rcp_f32_e32 v154, v154
	v_rcp_f32_e32 v155, v155
	v_rcp_f32_e32 v156, v156
	v_rcp_f32_e32 v157, v157
	v_mul_f32_e32 v150, v126, v150
	v_mul_f32_e32 v151, v127, v151
	v_mul_f32_e32 v152, v128, v152
	v_mul_f32_e32 v153, v129, v153
	v_mul_f32_e32 v154, v118, v154
	v_mul_f32_e32 v155, v119, v155
	v_mul_f32_e32 v156, v120, v156
	v_mul_f32_e32 v157, v121, v157
	v_mul_f32_e32 v122, v150, v122
	v_mul_f32_e32 v123, v151, v123
	v_mul_f32_e32 v124, v152, v124
	v_mul_f32_e32 v125, v153, v125
	v_mul_f32_e32 v114, v154, v114
	v_mul_f32_e32 v115, v155, v115
	v_mul_f32_e32 v116, v156, v116
	v_mul_f32_e32 v117, v157, v117
	v_cvt_pk_bf16_f32 v122, v122, v123
	v_cvt_pk_bf16_f32 v123, v124, v125
	v_cvt_pk_bf16_f32 v124, v114, v115
	v_cvt_pk_bf16_f32 v125, v116, v117
	flat_store_dwordx4 v[140:141], v[122:125]
	v_mul_f32_e32 v158, 0xbfb8aa3b, v110
	v_mul_f32_e32 v159, 0xbfb8aa3b, v111
	v_mul_f32_e32 v160, 0xbfb8aa3b, v112
	v_mul_f32_e32 v161, 0xbfb8aa3b, v113
	v_mul_f32_e32 v162, 0xbfb8aa3b, v102
	v_mul_f32_e32 v163, 0xbfb8aa3b, v103
	v_mul_f32_e32 v164, 0xbfb8aa3b, v104
	v_mul_f32_e32 v165, 0xbfb8aa3b, v105
	v_exp_f32_e32 v158, v158
	v_exp_f32_e32 v159, v159
	v_exp_f32_e32 v160, v160
	v_exp_f32_e32 v161, v161
	v_exp_f32_e32 v162, v162
	v_exp_f32_e32 v163, v163
	v_exp_f32_e32 v164, v164
	v_exp_f32_e32 v165, v165
	v_add_co_u32_e32 v166, vcc, 0x800, v140
	v_add_f32_e32 v158, 1.0, v158
	v_add_f32_e32 v159, 1.0, v159
	v_add_f32_e32 v160, 1.0, v160
	v_add_f32_e32 v161, 1.0, v161
	v_add_f32_e32 v162, 1.0, v162
	v_add_f32_e32 v163, 1.0, v163
	v_add_f32_e32 v164, 1.0, v164
	v_add_f32_e32 v165, 1.0, v165
	v_addc_co_u32_e32 v167, vcc, 0, v141, vcc
	v_rcp_f32_e32 v158, v158
	v_rcp_f32_e32 v159, v159
	v_rcp_f32_e32 v160, v160
	v_rcp_f32_e32 v161, v161
	v_rcp_f32_e32 v162, v162
	v_rcp_f32_e32 v163, v163
	v_rcp_f32_e32 v164, v164
	v_rcp_f32_e32 v165, v165
	v_mul_f32_e32 v158, v110, v158
	v_mul_f32_e32 v159, v111, v159
	v_mul_f32_e32 v160, v112, v160
	v_mul_f32_e32 v161, v113, v161
	v_mul_f32_e32 v162, v102, v162
	v_mul_f32_e32 v163, v103, v163
	v_mul_f32_e32 v164, v104, v164
	v_mul_f32_e32 v165, v105, v165
	v_mul_f32_e32 v106, v158, v106
	v_mul_f32_e32 v107, v159, v107
	v_mul_f32_e32 v108, v160, v108
	v_mul_f32_e32 v109, v161, v109
	v_mul_f32_e32 v98, v162, v98
	v_mul_f32_e32 v99, v163, v99
	v_mul_f32_e32 v100, v164, v100
	v_mul_f32_e32 v101, v165, v101
	v_cvt_pk_bf16_f32 v106, v106, v107
	v_cvt_pk_bf16_f32 v107, v108, v109
	v_cvt_pk_bf16_f32 v108, v98, v99
	v_cvt_pk_bf16_f32 v109, v100, v101
	flat_store_dwordx4 v[166:167], v[106:109]
	v_mul_f32_e32 v150, 0xbfb8aa3b, v94
	v_mul_f32_e32 v151, 0xbfb8aa3b, v95
	v_mul_f32_e32 v152, 0xbfb8aa3b, v96
	v_mul_f32_e32 v153, 0xbfb8aa3b, v97
	v_mul_f32_e32 v154, 0xbfb8aa3b, v86
	v_mul_f32_e32 v155, 0xbfb8aa3b, v87
	v_mul_f32_e32 v156, 0xbfb8aa3b, v88
	v_mul_f32_e32 v157, 0xbfb8aa3b, v89
	v_exp_f32_e32 v150, v150
	v_exp_f32_e32 v151, v151
	v_exp_f32_e32 v152, v152
	v_exp_f32_e32 v153, v153
	v_exp_f32_e32 v154, v154
	v_exp_f32_e32 v155, v155
	v_exp_f32_e32 v156, v156
	v_exp_f32_e32 v157, v157
	v_add_co_u32_e32 v148, vcc, 0x1000, v140
	v_add_f32_e32 v150, 1.0, v150
	v_add_f32_e32 v151, 1.0, v151
	v_add_f32_e32 v152, 1.0, v152
	v_add_f32_e32 v153, 1.0, v153
	v_add_f32_e32 v154, 1.0, v154
	v_add_f32_e32 v155, 1.0, v155
	v_add_f32_e32 v156, 1.0, v156
	v_add_f32_e32 v157, 1.0, v157
	v_addc_co_u32_e32 v149, vcc, 0, v141, vcc
	v_rcp_f32_e32 v150, v150
	v_rcp_f32_e32 v151, v151
	v_rcp_f32_e32 v152, v152
	v_rcp_f32_e32 v153, v153
	v_rcp_f32_e32 v154, v154
	v_rcp_f32_e32 v155, v155
	v_rcp_f32_e32 v156, v156
	v_rcp_f32_e32 v157, v157
	v_mul_f32_e32 v150, v94, v150
	v_mul_f32_e32 v151, v95, v151
	v_mul_f32_e32 v152, v96, v152
	v_mul_f32_e32 v153, v97, v153
	v_mul_f32_e32 v154, v86, v154
	v_mul_f32_e32 v155, v87, v155
	v_mul_f32_e32 v156, v88, v156
	v_mul_f32_e32 v157, v89, v157
	v_mul_f32_e32 v90, v150, v90
	v_mul_f32_e32 v91, v151, v91
	v_mul_f32_e32 v92, v152, v92
	v_mul_f32_e32 v93, v153, v93
	v_mul_f32_e32 v82, v154, v82
	v_mul_f32_e32 v83, v155, v83
	v_mul_f32_e32 v84, v156, v84
	v_mul_f32_e32 v85, v157, v85
	v_cvt_pk_bf16_f32 v90, v90, v91
	v_cvt_pk_bf16_f32 v91, v92, v93
	v_cvt_pk_bf16_f32 v92, v82, v83
	v_cvt_pk_bf16_f32 v93, v84, v85
	flat_store_dwordx4 v[148:149], v[90:93]
	v_mul_f32_e32 v158, 0xbfb8aa3b, v78
	v_mul_f32_e32 v159, 0xbfb8aa3b, v79
; __device__ __forceinline__ unsigned cvt_pk_bf16(float lo, float hi) { const pk_f2_t v = {lo, hi}; return __builtin_bit_cast(unsigned, __builtin_convertvector(v, pk_bf2_t)); }
; __device__ __forceinline__ float silu_f(float g) { return g * __builtin_amdgcn_rcpf(1.0f + __builtin_amdgcn_exp2f(-1.4426950408889634f * g)); }
;     __device__ __forceinline__ void operator()(const pg8::f32x4 (&acc)[2][2][4][2], const pg8::Unit& u, int wr, int wc, int fr, int fq) const {
;     ...
;             for (int m = 0; m < 4; ++m) {
;                 pg8::u32x4 w;
;                 { const pg8::f32x4 g = acc[ai][0][m][0], uu = acc[ai][1][m][0];
;                   w.x = pg8::cvt_pk_bf16(silu_f(g[0]) * uu[0], silu_f(g[1]) * uu[1]); w.y = pg8::cvt_pk_bf16(silu_f(g[2]) * uu[2], silu_f(g[3]) * uu[3]); }
;                 { const pg8::f32x4 g = acc[ai][0][m][1], uu = acc[ai][1][m][1];
;                   w.z = pg8::cvt_pk_bf16(silu_f(g[0]) * uu[0], silu_f(g[1]) * uu[1]); w.w = pg8::cvt_pk_bf16(silu_f(g[2]) * uu[2], silu_f(g[3]) * uu[3]); }
;                 *(pg8::u32x4*)(base + (size_t)(ai * 128 + m * 16) * FF) = w;
;                 asm volatile("" ::: "memory");
;             }
	v_mul_f32_e32 v160, 0xbfb8aa3b, v80
	v_mul_f32_e32 v161, 0xbfb8aa3b, v81
	v_mul_f32_e32 v162, 0xbfb8aa3b, v70
	v_mul_f32_e32 v163, 0xbfb8aa3b, v71
	v_mul_f32_e32 v164, 0xbfb8aa3b, v72
	v_mul_f32_e32 v165, 0xbfb8aa3b, v73
	v_exp_f32_e32 v158, v158
	v_exp_f32_e32 v159, v159
	v_exp_f32_e32 v160, v160
	v_exp_f32_e32 v161, v161
	v_exp_f32_e32 v162, v162
	v_exp_f32_e32 v163, v163
	v_exp_f32_e32 v164, v164
	v_exp_f32_e32 v165, v165
	v_add_co_u32_e32 v166, vcc, 0x1800, v140
	v_add_f32_e32 v158, 1.0, v158
	v_add_f32_e32 v159, 1.0, v159
	v_add_f32_e32 v160, 1.0, v160
	v_add_f32_e32 v161, 1.0, v161
	v_add_f32_e32 v162, 1.0, v162
	v_add_f32_e32 v163, 1.0, v163
	v_add_f32_e32 v164, 1.0, v164
	v_add_f32_e32 v165, 1.0, v165
	v_addc_co_u32_e32 v167, vcc, 0, v141, vcc
	v_rcp_f32_e32 v158, v158
	v_rcp_f32_e32 v159, v159
	v_rcp_f32_e32 v160, v160
	v_rcp_f32_e32 v161, v161
	v_rcp_f32_e32 v162, v162
	v_rcp_f32_e32 v163, v163
	v_rcp_f32_e32 v164, v164
	v_rcp_f32_e32 v165, v165
	v_mul_f32_e32 v158, v78, v158
	v_mul_f32_e32 v159, v79, v159
	v_mul_f32_e32 v160, v80, v160
	v_mul_f32_e32 v161, v81, v161
	v_mul_f32_e32 v162, v70, v162
	v_mul_f32_e32 v163, v71, v163
	v_mul_f32_e32 v164, v72, v164
	v_mul_f32_e32 v165, v73, v165
	v_mul_f32_e32 v74, v158, v74
	v_mul_f32_e32 v75, v159, v75
	v_mul_f32_e32 v76, v160, v76
	v_mul_f32_e32 v77, v161, v77
	v_mul_f32_e32 v66, v162, v66
	v_mul_f32_e32 v67, v163, v67
	v_mul_f32_e32 v68, v164, v68
	v_mul_f32_e32 v69, v165, v69
	v_cvt_pk_bf16_f32 v74, v74, v75
	v_cvt_pk_bf16_f32 v75, v76, v77
	v_cvt_pk_bf16_f32 v76, v66, v67
	v_cvt_pk_bf16_f32 v77, v68, v69
	flat_store_dwordx4 v[166:167], v[74:77]
	v_mul_f32_e32 v150, 0xbfb8aa3b, v62
	v_mul_f32_e32 v151, 0xbfb8aa3b, v63
	v_mul_f32_e32 v152, 0xbfb8aa3b, v64
	v_mul_f32_e32 v153, 0xbfb8aa3b, v65
	v_mul_f32_e32 v154, 0xbfb8aa3b, v54
	v_mul_f32_e32 v155, 0xbfb8aa3b, v55
	v_mul_f32_e32 v156, 0xbfb8aa3b, v56
	v_mul_f32_e32 v157, 0xbfb8aa3b, v57
	v_exp_f32_e32 v150, v150
	v_exp_f32_e32 v151, v151
	v_exp_f32_e32 v152, v152
	v_exp_f32_e32 v153, v153
	v_exp_f32_e32 v154, v154
	v_exp_f32_e32 v155, v155
	v_exp_f32_e32 v156, v156
	v_exp_f32_e32 v157, v157
	v_add_co_u32_e32 v148, vcc, 0x4000, v140
	v_add_f32_e32 v150, 1.0, v150
	v_add_f32_e32 v151, 1.0, v151
	v_add_f32_e32 v152, 1.0, v152
	v_add_f32_e32 v153, 1.0, v153
	v_add_f32_e32 v154, 1.0, v154
	v_add_f32_e32 v155, 1.0, v155
	v_add_f32_e32 v156, 1.0, v156
	v_add_f32_e32 v157, 1.0, v157
	v_addc_co_u32_e32 v149, vcc, 0, v141, vcc
	v_rcp_f32_e32 v150, v150
	v_rcp_f32_e32 v151, v151
	v_rcp_f32_e32 v152, v152
	v_rcp_f32_e32 v153, v153
	v_rcp_f32_e32 v154, v154
	v_rcp_f32_e32 v155, v155
	v_rcp_f32_e32 v156, v156
	v_rcp_f32_e32 v157, v157
	v_mul_f32_e32 v150, v62, v150
	v_mul_f32_e32 v151, v63, v151
	v_mul_f32_e32 v152, v64, v152
	v_mul_f32_e32 v153, v65, v153
	v_mul_f32_e32 v154, v54, v154
	v_mul_f32_e32 v155, v55, v155
	v_mul_f32_e32 v156, v56, v156
	v_mul_f32_e32 v157, v57, v157
	v_mul_f32_e32 v58, v150, v58
	v_mul_f32_e32 v59, v151, v59
	v_mul_f32_e32 v60, v152, v60
	v_mul_f32_e32 v61, v153, v61
	v_mul_f32_e32 v50, v154, v50
	v_mul_f32_e32 v51, v155, v51
	v_mul_f32_e32 v52, v156, v52
	v_mul_f32_e32 v53, v157, v53
	v_cvt_pk_bf16_f32 v58, v58, v59
	v_cvt_pk_bf16_f32 v59, v60, v61
	v_cvt_pk_bf16_f32 v60, v50, v51
	v_cvt_pk_bf16_f32 v61, v52, v53
	flat_store_dwordx4 v[148:149], v[58:61]
	v_mul_f32_e32 v158, 0xbfb8aa3b, v46
	v_mul_f32_e32 v159, 0xbfb8aa3b, v47
	v_mul_f32_e32 v160, 0xbfb8aa3b, v48
	v_mul_f32_e32 v161, 0xbfb8aa3b, v49
	v_mul_f32_e32 v162, 0xbfb8aa3b, v38
	v_mul_f32_e32 v163, 0xbfb8aa3b, v39
	v_mul_f32_e32 v164, 0xbfb8aa3b, v40
	v_mul_f32_e32 v165, 0xbfb8aa3b, v41
	v_exp_f32_e32 v158, v158
	v_exp_f32_e32 v159, v159
	v_exp_f32_e32 v160, v160
	v_exp_f32_e32 v161, v161
	v_exp_f32_e32 v162, v162
	v_exp_f32_e32 v163, v163
	v_exp_f32_e32 v164, v164
	v_exp_f32_e32 v165, v165
	v_add_co_u32_e32 v166, vcc, 0x4800, v140
	v_add_f32_e32 v158, 1.0, v158
	v_add_f32_e32 v159, 1.0, v159
	v_add_f32_e32 v160, 1.0, v160
	v_add_f32_e32 v161, 1.0, v161
	v_add_f32_e32 v162, 1.0, v162
	v_add_f32_e32 v163, 1.0, v163
	v_add_f32_e32 v164, 1.0, v164
	v_add_f32_e32 v165, 1.0, v165
	v_addc_co_u32_e32 v167, vcc, 0, v141, vcc
	v_rcp_f32_e32 v158, v158
	v_rcp_f32_e32 v159, v159
	v_rcp_f32_e32 v160, v160
	v_rcp_f32_e32 v161, v161
; __device__ __forceinline__ unsigned cvt_pk_bf16(float lo, float hi) { const pk_f2_t v = {lo, hi}; return __builtin_bit_cast(unsigned, __builtin_convertvector(v, pk_bf2_t)); }
; #define PG8_BAR __builtin_amdgcn_s_barrier()
; __device__ __forceinline__ float silu_f(float g) { return g * __builtin_amdgcn_rcpf(1.0f + __builtin_amdgcn_exp2f(-1.4426950408889634f * g)); }
; template <class Epi, class Sched, bool ALIGN_EPI = false, bool SP2 = false>
; __device__ __forceinline__ void gemm_phase(PG8_LAS unsigned char* lds, const Gemm g, const Sched& S, const Epi& E, int wave_s) {
;     ...
;         E(acc, cur, wr, wc, fr, fq); S.done(cur);
;         if (!has_next) break;
; #pragma unroll
;         for (int a = 0; a < 2; ++a)
; #pragma unroll
;             for (int b = 0; b < 2; ++b)
; #pragma unroll
;                 for (int m = 0; m < 4; ++m)
; #pragma unroll
;                     for (int n = 0; n < 2; ++n) acc[a][b][m][n] = (f32x4){0.f, 0.f, 0.f, 0.f};
;         cur = nxt; cA = nA; cB = nB; ++ui;
;         if constexpr (ALIGN_EPI) { if (wr == 1) PG8_BAR; }
;     __device__ __forceinline__ void operator()(const pg8::f32x4 (&acc)[2][2][4][2], const pg8::Unit& u, int wr, int wc, int fr, int fq) const {
;     ...
;             for (int m = 0; m < 4; ++m) {
;                 pg8::u32x4 w;
;                 { const pg8::f32x4 g = acc[ai][0][m][0], uu = acc[ai][1][m][0];
;                   w.x = pg8::cvt_pk_bf16(silu_f(g[0]) * uu[0], silu_f(g[1]) * uu[1]); w.y = pg8::cvt_pk_bf16(silu_f(g[2]) * uu[2], silu_f(g[3]) * uu[3]); }
;                 { const pg8::f32x4 g = acc[ai][0][m][1], uu = acc[ai][1][m][1];
;                   w.z = pg8::cvt_pk_bf16(silu_f(g[0]) * uu[0], silu_f(g[1]) * uu[1]); w.w = pg8::cvt_pk_bf16(silu_f(g[2]) * uu[2], silu_f(g[3]) * uu[3]); }
;                 *(pg8::u32x4*)(base + (size_t)(ai * 128 + m * 16) * FF) = w;
;                 asm volatile("" ::: "memory");
;             }
	v_rcp_f32_e32 v162, v162
	v_rcp_f32_e32 v163, v163
	v_rcp_f32_e32 v164, v164
	v_rcp_f32_e32 v165, v165
	v_mul_f32_e32 v158, v46, v158
	v_mul_f32_e32 v159, v47, v159
	v_mul_f32_e32 v160, v48, v160
	v_mul_f32_e32 v161, v49, v161
	v_mul_f32_e32 v162, v38, v162
	v_mul_f32_e32 v163, v39, v163
	v_mul_f32_e32 v164, v40, v164
	v_mul_f32_e32 v165, v41, v165
	v_mul_f32_e32 v42, v158, v42
	v_mul_f32_e32 v43, v159, v43
	v_mul_f32_e32 v44, v160, v44
	v_mul_f32_e32 v45, v161, v45
	v_mul_f32_e32 v34, v162, v34
	v_mul_f32_e32 v35, v163, v35
	v_mul_f32_e32 v36, v164, v36
	v_mul_f32_e32 v37, v165, v37
	v_cvt_pk_bf16_f32 v42, v42, v43
	v_cvt_pk_bf16_f32 v43, v44, v45
	v_cvt_pk_bf16_f32 v44, v34, v35
	v_cvt_pk_bf16_f32 v45, v36, v37
	flat_store_dwordx4 v[166:167], v[42:45]
	v_mul_f32_e32 v150, 0xbfb8aa3b, v30
	v_mul_f32_e32 v151, 0xbfb8aa3b, v31
	v_mul_f32_e32 v152, 0xbfb8aa3b, v32
	v_mul_f32_e32 v153, 0xbfb8aa3b, v33
	v_mul_f32_e32 v154, 0xbfb8aa3b, v22
	v_mul_f32_e32 v155, 0xbfb8aa3b, v23
	v_mul_f32_e32 v156, 0xbfb8aa3b, v24
	v_mul_f32_e32 v157, 0xbfb8aa3b, v25
	v_exp_f32_e32 v150, v150
	v_exp_f32_e32 v151, v151
	v_exp_f32_e32 v152, v152
	v_exp_f32_e32 v153, v153
	v_exp_f32_e32 v154, v154
	v_exp_f32_e32 v155, v155
	v_exp_f32_e32 v156, v156
	v_exp_f32_e32 v157, v157
	v_add_co_u32_e32 v148, vcc, 0x5000, v140
	v_add_f32_e32 v150, 1.0, v150
	v_add_f32_e32 v151, 1.0, v151
	v_add_f32_e32 v152, 1.0, v152
	v_add_f32_e32 v153, 1.0, v153
	v_add_f32_e32 v154, 1.0, v154
	v_add_f32_e32 v155, 1.0, v155
	v_add_f32_e32 v156, 1.0, v156
	v_add_f32_e32 v157, 1.0, v157
	v_addc_co_u32_e32 v149, vcc, 0, v141, vcc
	v_rcp_f32_e32 v150, v150
	v_rcp_f32_e32 v151, v151
	v_rcp_f32_e32 v152, v152
	v_rcp_f32_e32 v153, v153
	v_rcp_f32_e32 v154, v154
	v_rcp_f32_e32 v155, v155
	v_rcp_f32_e32 v156, v156
	v_rcp_f32_e32 v157, v157
	v_mul_f32_e32 v150, v30, v150
	v_mul_f32_e32 v151, v31, v151
	v_mul_f32_e32 v152, v32, v152
	v_mul_f32_e32 v153, v33, v153
	v_mul_f32_e32 v154, v22, v154
	v_mul_f32_e32 v155, v23, v155
	v_mul_f32_e32 v156, v24, v156
	v_mul_f32_e32 v157, v25, v157
	v_mul_f32_e32 v26, v150, v26
	v_mul_f32_e32 v27, v151, v27
	v_mul_f32_e32 v28, v152, v28
	v_mul_f32_e32 v29, v153, v29
	v_mul_f32_e32 v18, v154, v18
	v_mul_f32_e32 v19, v155, v19
	v_mul_f32_e32 v20, v156, v20
	v_mul_f32_e32 v21, v157, v21
	v_cvt_pk_bf16_f32 v26, v26, v27
	v_cvt_pk_bf16_f32 v27, v28, v29
	v_cvt_pk_bf16_f32 v28, v18, v19
	v_cvt_pk_bf16_f32 v29, v20, v21
	flat_store_dwordx4 v[148:149], v[26:29]
	v_mul_f32_e32 v158, 0xbfb8aa3b, v14
	v_mul_f32_e32 v159, 0xbfb8aa3b, v15
	v_mul_f32_e32 v160, 0xbfb8aa3b, v16
	v_mul_f32_e32 v161, 0xbfb8aa3b, v17
	v_mul_f32_e32 v162, 0xbfb8aa3b, v6
	v_mul_f32_e32 v163, 0xbfb8aa3b, v7
	v_mul_f32_e32 v164, 0xbfb8aa3b, v8
	v_mul_f32_e32 v165, 0xbfb8aa3b, v9
	v_exp_f32_e32 v158, v158
	v_exp_f32_e32 v159, v159
	v_exp_f32_e32 v160, v160
	v_exp_f32_e32 v161, v161
	v_exp_f32_e32 v162, v162
	v_exp_f32_e32 v163, v163
	v_exp_f32_e32 v164, v164
	v_exp_f32_e32 v165, v165
	v_add_co_u32_e32 v166, vcc, 0x5800, v140
	v_add_f32_e32 v158, 1.0, v158
	v_add_f32_e32 v159, 1.0, v159
	v_add_f32_e32 v160, 1.0, v160
	v_add_f32_e32 v161, 1.0, v161
	v_add_f32_e32 v162, 1.0, v162
	v_add_f32_e32 v163, 1.0, v163
	v_add_f32_e32 v164, 1.0, v164
	v_add_f32_e32 v165, 1.0, v165
	v_addc_co_u32_e32 v167, vcc, 0, v141, vcc
	v_rcp_f32_e32 v158, v158
	v_rcp_f32_e32 v159, v159
	v_rcp_f32_e32 v160, v160
	v_rcp_f32_e32 v161, v161
	v_rcp_f32_e32 v162, v162
	v_rcp_f32_e32 v163, v163
	v_rcp_f32_e32 v164, v164
	v_rcp_f32_e32 v165, v165
	v_mul_f32_e32 v158, v14, v158
	v_mul_f32_e32 v159, v15, v159
	v_mul_f32_e32 v160, v16, v160
	v_mul_f32_e32 v161, v17, v161
	v_mul_f32_e32 v162, v6, v162
	v_mul_f32_e32 v163, v7, v163
	v_mul_f32_e32 v164, v8, v164
	v_mul_f32_e32 v165, v9, v165
	v_mul_f32_e32 v10, v158, v10
	v_mul_f32_e32 v11, v159, v11
	v_mul_f32_e32 v12, v160, v12
	v_mul_f32_e32 v13, v161, v13
	v_mul_f32_e32 v2, v162, v2
	v_mul_f32_e32 v3, v163, v3
	v_mul_f32_e32 v4, v164, v4
	v_mul_f32_e32 v5, v165, v5
	v_cvt_pk_bf16_f32 v10, v10, v11
	v_cvt_pk_bf16_f32 v11, v12, v13
	v_cvt_pk_bf16_f32 v12, v2, v3
	v_cvt_pk_bf16_f32 v13, v4, v5
	flat_store_dwordx4 v[166:167], v[10:13]
	s_andn2_b64 vcc, exec, s[38:39]
	s_cbranch_vccnz .LBB0_275
	s_andn2_b64 vcc, exec, s[0:1]
	s_cbranch_vccnz .LBB0_274
	s_barrier
	s_branch .LBB0_274

; #define PG8_STAGE(bufoff, gbase, voff) do { _Pragma("unroll") for (int _i = 0; _i < 2; ++_i) \
;         __builtin_amdgcn_global_load_lds((const unsigned*)((const char*)(gbase) + (voff)[_i]), (PG8_LAS unsigned*)(lds + (bufoff) + ldsw + _i * 8192), 16, 0, 0); } while (0)
; #define PG8_BAR __builtin_amdgcn_s_barrier()
; template <class Epi, class Sched, bool ALIGN_EPI = false, bool SP2 = false>
; __device__ __forceinline__ void gemm_phase(PG8_LAS unsigned char* lds, const Gemm g, const Sched& S, const Epi& E, int wave_s) {
;     ...
;     const int tid = tid_, wid = __builtin_amdgcn_readfirstlane(tid >> 6), lane = tid & 63, wr = wid >> 2, wc = wid & 3, fr = lane & 15, fq = lane >> 4;
;     const int K = g.K, nt = K / BK;
;     unsigned voffA[2], voffB[2];
; #pragma unroll
;     for (int i = 0; i < 2; ++i) { int R, C; stage_rc(tid * 16 + i * 8192, R, C); const int Rb = Epi::PERM ? ((R & ~31) + perm32(R & 31)) : R;
;         voffA[i] = (unsigned)(R * g.lda + C) * 2u; voffB[i] = (unsigned)(Rb * g.ldb + C) * 2u; }
;     const size_t kstep = (size_t)(BK * 2);
;     const size_t hstepA = (size_t)HALF * g.lda * 2, hstepB = (size_t)HALF * g.ldb * 2;
;     const size_t tstepA = 2 * hstepA, tstepB = 2 * hstepB;
;     const unsigned ldsw = (unsigned)wid * 1024u;
;     const int aoff = lds_byte(wr * 64 + fr, fq * 8), boff = lds_byte(wc * 32 + fr, fq * 8);
;     ...
;     Unit cur, nxt; int ui = 0;
;     if (!S.next(0, cur)) return;
;     f32x4 acc[2][2][4][2];
; #pragma unroll
;     for (int a = 0; a < 2; ++a)
; #pragma unroll
;         for (int b = 0; b < 2; ++b)
; #pragma unroll
;             for (int m = 0; m < 4; ++m)
; #pragma unroll
;                 for (int n = 0; n < 2; ++n) acc[a][b][m][n] = (f32x4){0.f, 0.f, 0.f, 0.f};
;     bf16x8 At[4][2], B0[2][2], B1[2][2];
;     const char* cA = (const char*)g.A + (size_t)cur.pm * tstepA; const char* cB = (const char*)g.Bt + (size_t)cur.pn * tstepB;
;     S.a_ready(cur);
;     if constexpr (SP2) {
;         PG8_STAGE(PG8_SB(0, 0), cB, voffB); PG8_STAGE(PG8_SB(0, 1), cB + hstepB, voffB); PG8_STAGE(PG8_SA(0, 0), cA, voffA); PG8_STAGE(PG8_SA(0, 1), cA + hstepA, voffA);
;         if (wr == 1) PG8_BAR;
;         PG8_WAIT_V(2); PG8_BAR;
;         PG8_STAGE(PG8_SB(1, 0), cB + kstep, voffB); PG8_STAGE(PG8_SA(1, 0), cA + kstep, voffA); PG8_STAGE(PG8_SB(1, 1), cB + hstepB + kstep, voffB);
;         PG8_WAIT_V(6); PG8_BAR;
.LBB0_341:
	v_mov_b32_e32 v0, v1
	s_andn2_b32 s2, s2, 63
	v_mbcnt_lo_u32_b32 v0, -1, v0
	v_mbcnt_hi_u32_b32 v0, -1, v0
	v_readlane_b32 s6, v254, 2
	v_or_b32_e32 v18, s2, v0
	v_readlane_b32 s7, v254, 3
	s_andn2_b64 vcc, exec, s[6:7]
	v_readfirstlane_b32 s12, v18
	s_cbranch_vccnz .LBB0_365
	v_lshlrev_b32_e32 v0, 4, v18
	v_add_u32_e32 v2, 0x2000, v0
	v_ashrrev_i32_e32 v3, 31, v2
	v_lshrrev_b32_e32 v3, 22, v3
	v_add_u32_e32 v3, v2, v3
	v_ashrrev_i32_e32 v10, 10, v3
	v_mul_i32_i24_e32 v3, 0x400, v10
	v_sub_u32_e32 v2, v2, v3
	v_lshrrev_b32_e32 v3, 4, v2
	v_bitop3_b32 v2, v3, v2, 32 bitop3:0x6c
	v_ashrrev_i32_e32 v3, 31, v2
	v_lshrrev_b32_e32 v3, 26, v3
	v_add_u32_e32 v3, v2, v3
	v_ashrrev_i32_e32 v11, 6, v3
	v_lshlrev_b32_e32 v5, 5, v10
	v_and_b32_e32 v3, 0xc0, v3
	v_and_b32_e32 v12, 32, v5
	v_sub_u32_e32 v2, v2, v3
	v_mov_b32_e32 v5, 1
	v_ashrrev_i16_sdwa v2, v5, sext(v2) dst_sel:DWORD dst_unused:UNUSED_PAD src0_sel:DWORD src1_sel:BYTE_0
	v_bfe_i32 v13, v2, 0, 16
	v_bfe_i32 v2, v18, 27, 1
	v_lshrrev_b32_e32 v2, 22, v2
	v_add_u32_e32 v2, v0, v2
	v_and_b32_e32 v2, 0xfffffc00, v2
	v_sub_u32_e32 v0, v0, v2
	s_add_u32 s2, s10, 0x22d90000
	v_lshrrev_b32_e32 v2, 4, v0
	v_ashrrev_i32_e32 v3, 31, v18
	s_addc_u32 s22, s11, 0
	s_mul_i32 s6, s78, 0x2c00000
	v_bitop3_b32 v0, v2, v0, 32 bitop3:0x6c
	v_lshrrev_b32_e32 v3, 26, v3
	s_add_u32 s6, s10, s6
	v_lshlrev_b32_e32 v4, 3, v10
	v_ashrrev_i32_e32 v2, 31, v0
	v_add_u32_e32 v3, v18, v3
	s_addc_u32 s7, s11, 0
	v_and_b32_e32 v4, 0x7ffff0, v4
	v_lshrrev_b32_e32 v2, 26, v2
	v_ashrrev_i32_e32 v15, 6, v3
	s_add_u32 s33, s6, 0xb190000
	v_add_u32_e32 v4, v11, v4
	s_movk_i32 s6, 0x1600
	v_add_u32_e32 v2, v0, v2
	v_lshlrev_b32_e32 v3, 3, v15
	v_lshl_or_b32 v228, v4, 6, v12
	v_add_lshl_u32 v228, v228, v13, 1
	v_mov_b32_e32 v229, 0
	v_mul_lo_u32 v4, v4, s6
	v_ashrrev_i32_e32 v14, 6, v2
	v_and_b32_e32 v3, 0x7ffff0, v3
	s_addc_u32 s36, s7, 0
	s_ashr_i32 s13, s12, 6
	v_or_b32_e32 v4, v4, v12
	v_add_u32_e32 v3, v14, v3
	v_and_b32_e32 v2, 0xc0, v2
	s_ashr_i32 s14, s12, 8
	s_lshl_b32 s37, s13, 10
	s_waitcnt vmcnt(0)
	v_add_lshl_u32 v130, v4, v13, 1
	v_mov_b32_e32 v226, v3
	v_mul_lo_u32 v3, v3, s6
	v_lshlrev_b32_e32 v4, 5, v15
	v_sub_u32_e32 v0, v0, v2
	v_readlane_b32 s6, v255, 22
	v_and_b32_e32 v16, 32, v4
	v_ashrrev_i16_sdwa v0, v5, sext(v0) dst_sel:DWORD dst_unused:UNUSED_PAD src0_sel:DWORD src1_sel:BYTE_0
	s_add_u32 s18, s33, s6
	v_readlane_b32 s6, v255, 20
	v_or_b32_e32 v3, v3, v16
	v_bfe_i32 v17, v0, 0, 16
	s_addc_u32 s19, s36, s6
	s_add_i32 s42, s37, 0
	v_add_lshl_u32 v0, v3, v17, 1
	v_lshl_or_b32 v226, v226, 6, v16
	v_add_lshl_u32 v226, v226, v17, 1
	v_mov_b32_e32 v227, 0
	s_add_i32 m0, s42, 0x10000
	v_mov_b32_e32 v131, v1
	global_load_lds_dwordx4 v0, s[18:19]
	s_add_i32 m0, s42, 0x12000
	s_add_u32 s6, s18, 0x160000
	global_load_lds_dwordx4 v130, s[18:19]
	s_addc_u32 s7, s19, 0
	s_add_i32 m0, s42, 0x14000
	v_lshl_add_u64 v[8:9], s[18:19], 0, v[0:1]
	global_load_lds_dwordx4 v0, s[6:7]
	s_add_i32 m0, s42, 0x16000
	v_lshl_add_u64 v[6:7], s[18:19], 0, v[130:131]
	global_load_lds_dwordx4 v130, s[6:7]
	v_readlane_b32 s6, v255, 19
	s_add_u32 s16, s2, s6
	v_readlane_b32 s6, v255, 16
	s_addc_u32 s17, s22, s6
	s_add_i32 s43, s42, 0x2000
	s_mov_b32 m0, s42
	s_add_u32 s6, s16, 0x4000
	global_load_lds_dwordx4 v226, s[16:17]
	s_mov_b32 m0, s43
	s_addc_u32 s7, s17, 0
	s_add_i32 s44, s42, 0x4000
	global_load_lds_dwordx4 v228, s[16:17]
	s_mov_b32 m0, s44
	s_add_i32 s45, s42, 0x6000
	global_load_lds_dwordx4 v226, s[6:7]
	s_mov_b32 m0, s45
	s_cmp_eq_u32 s14, 1
	global_load_lds_dwordx4 v228, s[6:7]
	v_lshl_add_u64 v[2:3], s[16:17], 0, v[226:227]
	s_cselect_b64 s[6:7], -1, 0
	s_cmp_lg_u32 s14, 1
	v_lshl_add_u64 v[4:5], s[16:17], 0, v[228:229]
	s_cbranch_scc1 .LBB0_344
	s_barrier
.LBB0_344:
	s_add_u32 s8, s10, 0x16d90000
	s_addc_u32 s9, s11, 0
	s_mul_i32 s15, s78, 0x48000
	s_add_u32 s10, s10, s15
	s_addc_u32 s11, s11, 0
	v_bfe_u32 v19, v18, 4, 2
	s_add_u32 s46, s10, 0x104000
	v_and_b32_e32 v20, 15, v18
	v_lshlrev_b32_e32 v21, 4, v19
	v_lshlrev_b32_e32 v18, 2, v18
	s_addc_u32 s47, s11, 0
	v_lshl_or_b32 v158, s14, 6, v20
	v_lshl_or_b32 v20, v20, 6, v21
	s_lshl_b32 s10, s14, 13
	v_and_b32_e32 v18, 32, v18
	v_bitop3_b32 v21, v20, s10, v18 bitop3:0xde
	s_lshl_b32 s10, s13, 5
	s_and_b32 s13, s10, 0x60
	s_add_i32 m0, s42, 0x18000
	v_lshl_add_u64 v[8:9], v[8:9], 0, s[30:31]
	s_lshl_b32 s10, s13, 7
	s_waitcnt vmcnt(2)
	s_barrier
	global_load_lds_dwordx4 v[8:9], off
	v_lshl_add_u64 v[6:7], v[6:7], 0, s[30:31]
	s_add_i32 m0, s42, 0x1a000
	s_add_i32 s48, s42, 0x8000
	s_add_i32 s49, s42, 0xa000
	v_bitop3_b32 v159, v20, s10, v18 bitop3:0xde
	global_load_lds_dwordx4 v[6:7], off
	s_mov_b64 s[100:101], 0x8000
	v_lshl_add_u64 v[2:3], v[2:3], 0, s[100:101]
	s_mov_b32 m0, s48
	s_add_u32 s10, s18, 0x160080
	global_load_lds_dwordx4 v[2:3], off
	v_lshl_add_u64 v[2:3], v[4:5], 0, s[100:101]
	s_mov_b32 m0, s49
	s_addc_u32 s11, s19, 0
	global_load_lds_dwordx4 v[2:3], off
	s_add_i32 m0, s42, 0x1c000
	v_lshl_add_u64 v[2:3], s[10:11], 0, v[0:1]
	global_load_lds_dwordx4 v[2:3], off
	v_lshl_add_u64 v[2:3], s[10:11], 0, v[130:131]
	s_add_i32 m0, s42, 0x1e000
	s_movk_i32 s15, 0x1600
	global_load_lds_dwordx4 v[2:3], off
	v_lshrrev_b32_e32 v3, 1, v10
	v_mul_lo_u32 v2, v11, s15
	s_mov_b32 s14, 0x16000
	s_cmpk_lt_u32 s12, 0x100
	v_lshl_or_b32 v160, v19, 2, s13
	v_mad_u64_u32 v[2:3], s[12:13], v3, s14, v[2:3]
	v_or_b32_e32 v2, v2, v12
	v_add_lshl_u32 v2, v2, v13, 1
	v_mov_b32_e32 v3, v1
	s_mov_b64 s[20:21], 0x160080
	s_mov_b64 s[100:101], 0xc000
	v_lshl_add_u64 v[132:133], v[228:229], 0, s[100:101]
	v_lshrrev_b32_e32 v3, 1, v15
	v_mul_lo_u32 v2, v14, s15
	v_mad_u64_u32 v[2:3], s[12:13], v3, s14, v[2:3]
	s_waitcnt vmcnt(6)
	v_or_b32_e32 v2, v2, v16
	v_add_lshl_u32 v2, v2, v17, 1
	v_mov_b32_e32 v3, v1
	v_readlane_b32 s12, v255, 17
	s_cselect_b64 s[10:11], -1, 0
	v_lshl_add_u64 v[134:135], v[226:227], 0, s[100:101]
	s_mov_b32 s50, 0
	v_add_u32_e32 v161, 0, v21
	v_readlane_b32 s26, v255, 21
	s_mov_b32 s55, s12
	s_barrier
	v_readlane_b32 s13, v255, 18
	s_branch .LBB0_347

; #define PG8_STAGE(bufoff, gbase, voff) do { _Pragma("unroll") for (int _i = 0; _i < 2; ++_i) \
;         __builtin_amdgcn_global_load_lds((const unsigned*)((const char*)(gbase) + (voff)[_i]), (PG8_LAS unsigned*)(lds + (bufoff) + ldsw + _i * 8192), 16, 0, 0); } while (0)
; #define PG8_LDA(dst, b, h) do { _Pragma("unroll") for (int m = 0; m < 4; ++m) _Pragma("unroll") for (int k = 0; k < 2; ++k) dst[m][k] = *(const PG8_LAS bf16x8*)(lds + PG8_SA(b, h) + aoff + m * 2048 + k * 1024); } while (0)
; #define PG8_LDB(dst, b, h) do { _Pragma("unroll") for (int n = 0; n < 2; ++n) _Pragma("unroll") for (int k = 0; k < 2; ++k) dst[n][k] = *(const PG8_LAS bf16x8*)(lds + PG8_SB(b, h) + boff + n * 2048 + k * 1024); } while (0)
; #define PG8_MMA(ai, bj, At, Bt) do { __builtin_amdgcn_s_setprio(1); _Pragma("unroll") for (int m = 0; m < 4; ++m) _Pragma("unroll") for (int n = 0; n < 2; ++n) _Pragma("unroll") for (int k = 0; k < 2; ++k) \
;         acc[ai][bj][m][n] = __builtin_amdgcn_mfma_f32_16x16x32_bf16(Bt[n][k], At[m][k], acc[ai][bj][m][n], 0, 0, 0); __builtin_amdgcn_s_setprio(0); } while (0)
; template <class Epi, class Sched, bool ALIGN_EPI = false, bool SP2 = false>
; __device__ __forceinline__ void gemm_phase(PG8_LAS unsigned char* lds, const Gemm g, const Sched& S, const Epi& E, int wave_s) {
;     ...
;         for (int t = 0; t < nt; t += 2) {
;             const bool last = (t == nt - 2);
;             const char* a1 = cA + (size_t)(t + 1) * kstep;
;             const char* a2 = last ? nA : cA + (size_t)(t + 2) * kstep; const char* b2 = last ? nB : cB + (size_t)(t + 2) * kstep;
;             const char* a3 = a2 + kstep; const char* b3 = b2 + kstep;
;             if (last && has_next) S.a_ready(nxt);
;             if constexpr (Epi::HAS_MID) { if (t == nt / 2) E.mid(acc, cur, wr, wc, fr, fq); }
;             if constexpr (SP2) {
;             PG8_LDB(B0, 0, 0); PG8_LDB(B1, 0, 1); PG8_SCHED; PG8_LDA(At, 0, 0); PG8_STAGE(PG8_SA(1, 1), a1 + hstepA, voffA);
;             PG8_WAIT_V(8); PG8_WAIT_L(0); PG8_BAR; PG8_MMA(0, 0, At, B0); PG8_MMA(0, 1, At, B1); PG8_BAR; PG8_SCHED;
;             PG8_LDA(At, 0, 1); PG8_STAGE(PG8_SB(0, 0), b2, voffB); PG8_STAGE(PG8_SB(0, 1), b2 + hstepB, voffB); PG8_STAGE(PG8_SA(0, 0), a2, voffA);
;             PG8_WAIT_V(8); PG8_WAIT_L(0); PG8_BAR; PG8_MMA(1, 0, At, B0); PG8_MMA(1, 1, At, B1); PG8_BAR; PG8_SCHED;
.LBB0_358:
	s_add_u32 s18, s16, 0x10000
	s_addc_u32 s19, s17, 0
	s_add_i32 s34, 0, 0x10000
	s_cmpk_eq_i32 s41, 0x54
	s_cselect_b32 s25, s13, s19
	s_cselect_b32 s24, s12, s18
	s_cselect_b32 s21, s15, s40
	s_cselect_b32 s20, s14, s27
	s_add_i32 s35, 0, 0x14000
	v_add_u32_e32 v148, s34, v159
	v_add_u32_e32 v156, s35, v159
	ds_read_b128 v[136:139], v148
	ds_read_b128 v[140:143], v148 offset:1024
	ds_read_b128 v[144:147], v148 offset:2048
	ds_read_b128 v[148:151], v148 offset:3072
	ds_read_b128 v[152:155], v156
	ds_read_b128 v[162:165], v156 offset:1024
	ds_read_b128 v[166:169], v156 offset:2048
	ds_read_b128 v[176:179], v156 offset:3072
	v_lshl_add_u64 v[156:157], s[16:17], 0, v[134:135]
	s_add_i32 m0, s42, 0xc000
	ds_read_b128 v[180:183], v161
	ds_read_b128 v[184:187], v161 offset:1024
	ds_read_b128 v[188:191], v161 offset:2048
	ds_read_b128 v[192:195], v161 offset:3072
	ds_read_b128 v[196:199], v161 offset:4096
	ds_read_b128 v[208:211], v161 offset:5120
	ds_read_b128 v[212:215], v161 offset:6144
	ds_read_b128 v[216:219], v161 offset:7168
	global_load_lds_dwordx4 v[156:157], off
	v_lshl_add_u64 v[156:157], s[16:17], 0, v[132:133]
	s_add_i32 m0, s42, 0xe000
	s_nop 0
	global_load_lds_dwordx4 v[156:157], off
	s_waitcnt vmcnt(8)
	s_waitcnt lgkmcnt(0)
	s_barrier
	s_setprio 1
	s_waitcnt lgkmcnt(0)
	v_mfma_f32_16x16x32_bf16 v[126:129], v[180:183], v[136:139], v[126:129]
	v_mfma_f32_16x16x32_bf16 v[122:125], v[180:183], v[144:147], v[122:125]
	v_mfma_f32_16x16x32_bf16 v[110:113], v[188:191], v[136:139], v[110:113]
	v_mfma_f32_16x16x32_bf16 v[106:109], v[188:191], v[144:147], v[106:109]
	v_mfma_f32_16x16x32_bf16 v[94:97], v[196:199], v[136:139], v[94:97]
	v_mfma_f32_16x16x32_bf16 v[90:93], v[196:199], v[144:147], v[90:93]
	v_mfma_f32_16x16x32_bf16 v[78:81], v[212:215], v[136:139], v[78:81]
	v_mfma_f32_16x16x32_bf16 v[74:77], v[212:215], v[144:147], v[74:77]
	v_mfma_f32_16x16x32_bf16 v[126:129], v[184:187], v[140:143], v[126:129]
	v_mfma_f32_16x16x32_bf16 v[122:125], v[184:187], v[148:151], v[122:125]
	v_mfma_f32_16x16x32_bf16 v[110:113], v[192:195], v[140:143], v[110:113]
	v_mfma_f32_16x16x32_bf16 v[106:109], v[192:195], v[148:151], v[106:109]
	v_mfma_f32_16x16x32_bf16 v[94:97], v[208:211], v[140:143], v[94:97]
	v_mfma_f32_16x16x32_bf16 v[90:93], v[208:211], v[148:151], v[90:93]
	v_mfma_f32_16x16x32_bf16 v[78:81], v[216:219], v[140:143], v[78:81]
	v_mfma_f32_16x16x32_bf16 v[74:77], v[216:219], v[148:151], v[74:77]
	s_setprio 0
	s_setprio 1
	v_mfma_f32_16x16x32_bf16 v[118:121], v[180:183], v[152:155], v[118:121]
	v_mfma_f32_16x16x32_bf16 v[114:117], v[180:183], v[166:169], v[114:117]
	v_mfma_f32_16x16x32_bf16 v[102:105], v[188:191], v[152:155], v[102:105]
	v_mfma_f32_16x16x32_bf16 v[98:101], v[188:191], v[166:169], v[98:101]
	v_mfma_f32_16x16x32_bf16 v[86:89], v[196:199], v[152:155], v[86:89]
	v_mfma_f32_16x16x32_bf16 v[82:85], v[196:199], v[166:169], v[82:85]
	v_mfma_f32_16x16x32_bf16 v[70:73], v[212:215], v[152:155], v[70:73]
	v_mfma_f32_16x16x32_bf16 v[66:69], v[212:215], v[166:169], v[66:69]
	v_mfma_f32_16x16x32_bf16 v[118:121], v[184:187], v[162:165], v[118:121]
	v_mfma_f32_16x16x32_bf16 v[114:117], v[184:187], v[176:179], v[114:117]
	v_mfma_f32_16x16x32_bf16 v[102:105], v[192:195], v[162:165], v[102:105]
	v_mfma_f32_16x16x32_bf16 v[98:101], v[192:195], v[176:179], v[98:101]
	v_mfma_f32_16x16x32_bf16 v[86:89], v[208:211], v[162:165], v[86:89]
	v_mfma_f32_16x16x32_bf16 v[82:85], v[208:211], v[176:179], v[82:85]
	v_mfma_f32_16x16x32_bf16 v[70:73], v[216:219], v[162:165], v[70:73]
	v_mfma_f32_16x16x32_bf16 v[66:69], v[216:219], v[176:179], v[66:69]
	s_setprio 0
	s_barrier
	s_add_i32 s16, s34, s37
	v_lshl_add_u64 v[156:157], s[20:21], 0, v[0:1]
	s_mov_b32 m0, s16
	ds_read_b128 v[180:183], v161 offset:16384
	ds_read_b128 v[184:187], v161 offset:17408
	ds_read_b128 v[188:191], v161 offset:18432
	ds_read_b128 v[192:195], v161 offset:19456
	ds_read_b128 v[196:199], v161 offset:20480
	ds_read_b128 v[208:211], v161 offset:21504
	ds_read_b128 v[212:215], v161 offset:22528
	ds_read_b128 v[216:219], v161 offset:23552
	global_load_lds_dwordx4 v[156:157], off
	s_add_i32 m0, s16, 0x2000
	s_add_u32 s16, s20, 0x160000
	v_lshl_add_u64 v[170:171], s[20:21], 0, v[130:131]
	s_addc_u32 s17, s21, 0
	s_add_i32 s34, s35, s37
	global_load_lds_dwordx4 v[170:171], off
	v_lshl_add_u64 v[200:201], s[16:17], 0, v[0:1]
	s_mov_b32 m0, s34
	v_lshl_add_u64 v[220:221], s[24:25], 0, v[228:229]
	global_load_lds_dwordx4 v[200:201], off
	v_lshl_add_u64 v[200:201], s[16:17], 0, v[130:131]
	s_add_i32 m0, s34, 0x2000
	s_nop 0
	global_load_lds_dwordx4 v[200:201], off
	v_lshl_add_u64 v[200:201], s[24:25], 0, v[226:227]
	s_mov_b32 m0, s42
	s_nop 0
	global_load_lds_dwordx4 v[200:201], off
	s_mov_b32 m0, s43
	s_nop 0
	global_load_lds_dwordx4 v[220:221], off
	s_waitcnt vmcnt(8)
	s_waitcnt lgkmcnt(0)
	s_barrier
; #define PG8_STAGE(bufoff, gbase, voff) do { _Pragma("unroll") for (int _i = 0; _i < 2; ++_i) \
;         __builtin_amdgcn_global_load_lds((const unsigned*)((const char*)(gbase) + (voff)[_i]), (PG8_LAS unsigned*)(lds + (bufoff) + ldsw + _i * 8192), 16, 0, 0); } while (0)
; #define PG8_LDA(dst, b, h) do { _Pragma("unroll") for (int m = 0; m < 4; ++m) _Pragma("unroll") for (int k = 0; k < 2; ++k) dst[m][k] = *(const PG8_LAS bf16x8*)(lds + PG8_SA(b, h) + aoff + m * 2048 + k * 1024); } while (0)
; #define PG8_LDB(dst, b, h) do { _Pragma("unroll") for (int n = 0; n < 2; ++n) _Pragma("unroll") for (int k = 0; k < 2; ++k) dst[n][k] = *(const PG8_LAS bf16x8*)(lds + PG8_SB(b, h) + boff + n * 2048 + k * 1024); } while (0)
; #define PG8_MMA(ai, bj, At, Bt) do { __builtin_amdgcn_s_setprio(1); _Pragma("unroll") for (int m = 0; m < 4; ++m) _Pragma("unroll") for (int n = 0; n < 2; ++n) _Pragma("unroll") for (int k = 0; k < 2; ++k) \
;         acc[ai][bj][m][n] = __builtin_amdgcn_mfma_f32_16x16x32_bf16(Bt[n][k], At[m][k], acc[ai][bj][m][n], 0, 0, 0); __builtin_amdgcn_s_setprio(0); } while (0)
; #define PG8_WAIT_V(n) asm volatile("s_waitcnt vmcnt(" #n ")" ::: "memory")
; #define PG8_WAIT_L(n) asm volatile("s_waitcnt lgkmcnt(" #n ")" ::: "memory")
; #define PG8_BAR __builtin_amdgcn_s_barrier()
; #define PG8_SCHED __builtin_amdgcn_sched_barrier(0)
; template <class Epi, class Sched, bool ALIGN_EPI = false, bool SP2 = false>
; __device__ __forceinline__ void gemm_phase(PG8_LAS unsigned char* lds, const Gemm g, const Sched& S, const Epi& E, int wave_s) {
;     ...
;             PG8_LDA(At, 0, 1); PG8_STAGE(PG8_SB(0, 0), b2, voffB); PG8_STAGE(PG8_SB(0, 1), b2 + hstepB, voffB); PG8_STAGE(PG8_SA(0, 0), a2, voffA);
;             PG8_WAIT_V(8); PG8_WAIT_L(0); PG8_BAR; PG8_MMA(1, 0, At, B0); PG8_MMA(1, 1, At, B1); PG8_BAR; PG8_SCHED;
;             PG8_LDB(B0, 1, 0); PG8_LDB(B1, 1, 1); PG8_SCHED; PG8_LDA(At, 1, 0); PG8_STAGE(PG8_SA(0, 1), a2 + hstepA, voffA);
;             PG8_WAIT_V(8); PG8_WAIT_L(0); PG8_BAR; PG8_MMA(0, 0, At, B0); PG8_MMA(0, 1, At, B1); PG8_BAR; PG8_SCHED;
;             PG8_LDA(At, 1, 1); PG8_STAGE(PG8_SB(1, 0), b3, voffB); PG8_STAGE(PG8_SB(1, 1), b3 + hstepB, voffB); PG8_STAGE(PG8_SA(1, 0), a3, voffA);
	s_setprio 1
	s_waitcnt lgkmcnt(0)
	v_mfma_f32_16x16x32_bf16 v[62:65], v[180:183], v[136:139], v[62:65]
	v_mfma_f32_16x16x32_bf16 v[58:61], v[180:183], v[144:147], v[58:61]
	v_mfma_f32_16x16x32_bf16 v[46:49], v[188:191], v[136:139], v[46:49]
	v_mfma_f32_16x16x32_bf16 v[42:45], v[188:191], v[144:147], v[42:45]
	v_mfma_f32_16x16x32_bf16 v[30:33], v[196:199], v[136:139], v[30:33]
	v_mfma_f32_16x16x32_bf16 v[26:29], v[196:199], v[144:147], v[26:29]
	v_mfma_f32_16x16x32_bf16 v[14:17], v[212:215], v[136:139], v[14:17]
	v_mfma_f32_16x16x32_bf16 v[10:13], v[212:215], v[144:147], v[10:13]
	v_mfma_f32_16x16x32_bf16 v[62:65], v[184:187], v[140:143], v[62:65]
	v_mfma_f32_16x16x32_bf16 v[58:61], v[184:187], v[148:151], v[58:61]
	v_mfma_f32_16x16x32_bf16 v[46:49], v[192:195], v[140:143], v[46:49]
	v_mfma_f32_16x16x32_bf16 v[42:45], v[192:195], v[148:151], v[42:45]
	v_mfma_f32_16x16x32_bf16 v[30:33], v[208:211], v[140:143], v[30:33]
	v_mfma_f32_16x16x32_bf16 v[26:29], v[208:211], v[148:151], v[26:29]
	v_mfma_f32_16x16x32_bf16 v[14:17], v[216:219], v[140:143], v[14:17]
	v_mfma_f32_16x16x32_bf16 v[10:13], v[216:219], v[148:151], v[10:13]
	s_setprio 0
	s_setprio 1
	v_mfma_f32_16x16x32_bf16 v[54:57], v[180:183], v[152:155], v[54:57]
	v_mfma_f32_16x16x32_bf16 v[50:53], v[180:183], v[166:169], v[50:53]
	v_mfma_f32_16x16x32_bf16 v[38:41], v[188:191], v[152:155], v[38:41]
	v_mfma_f32_16x16x32_bf16 v[34:37], v[188:191], v[166:169], v[34:37]
	v_mfma_f32_16x16x32_bf16 v[22:25], v[196:199], v[152:155], v[22:25]
	v_mfma_f32_16x16x32_bf16 v[18:21], v[196:199], v[166:169], v[18:21]
	v_mfma_f32_16x16x32_bf16 v[6:9], v[212:215], v[152:155], v[6:9]
	v_mfma_f32_16x16x32_bf16 v[2:5], v[212:215], v[166:169], v[2:5]
	v_mfma_f32_16x16x32_bf16 v[54:57], v[184:187], v[162:165], v[54:57]
	v_mfma_f32_16x16x32_bf16 v[50:53], v[184:187], v[176:179], v[50:53]
	v_mfma_f32_16x16x32_bf16 v[38:41], v[192:195], v[162:165], v[38:41]
	v_mfma_f32_16x16x32_bf16 v[34:37], v[192:195], v[176:179], v[34:37]
	v_mfma_f32_16x16x32_bf16 v[22:25], v[208:211], v[162:165], v[22:25]
	v_mfma_f32_16x16x32_bf16 v[18:21], v[208:211], v[176:179], v[18:21]
	v_mfma_f32_16x16x32_bf16 v[6:9], v[216:219], v[162:165], v[6:9]
	v_mfma_f32_16x16x32_bf16 v[2:5], v[216:219], v[176:179], v[2:5]
	s_setprio 0
	s_barrier
	s_add_i32 s34, 0, 0x18000
	s_add_i32 s35, 0, 0x1c000
	v_add_u32_e32 v148, s34, v159
	v_add_u32_e32 v176, s35, v159
	ds_read_b128 v[136:139], v148
	ds_read_b128 v[140:143], v148 offset:1024
	ds_read_b128 v[144:147], v148 offset:2048
	ds_read_b128 v[148:151], v148 offset:3072
	ds_read_b128 v[152:155], v176
	ds_read_b128 v[162:165], v176 offset:1024
	ds_read_b128 v[166:169], v176 offset:2048
	ds_read_b128 v[176:179], v176 offset:3072
	s_add_u32 s16, s24, 0x4000
	s_addc_u32 s17, s25, 0
	s_mov_b32 m0, s44
	v_lshl_add_u64 v[222:223], s[16:17], 0, v[226:227]
	ds_read_b128 v[180:183], v161 offset:32768
	ds_read_b128 v[184:187], v161 offset:33792
	ds_read_b128 v[188:191], v161 offset:34816
	ds_read_b128 v[192:195], v161 offset:35840
	ds_read_b128 v[196:199], v161 offset:36864
	ds_read_b128 v[208:211], v161 offset:37888
	ds_read_b128 v[212:215], v161 offset:38912
	ds_read_b128 v[216:219], v161 offset:39936
	global_load_lds_dwordx4 v[222:223], off
	v_lshl_add_u64 v[222:223], s[16:17], 0, v[228:229]
	s_mov_b32 m0, s45
	s_nop 0
	global_load_lds_dwordx4 v[222:223], off
	s_waitcnt vmcnt(8)
	s_waitcnt lgkmcnt(0)
	s_barrier
	s_setprio 1
	s_waitcnt lgkmcnt(0)
	v_mfma_f32_16x16x32_bf16 v[126:129], v[180:183], v[136:139], v[126:129]
	v_mfma_f32_16x16x32_bf16 v[122:125], v[180:183], v[144:147], v[122:125]
	v_mfma_f32_16x16x32_bf16 v[110:113], v[188:191], v[136:139], v[110:113]
	v_mfma_f32_16x16x32_bf16 v[106:109], v[188:191], v[144:147], v[106:109]
	v_mfma_f32_16x16x32_bf16 v[94:97], v[196:199], v[136:139], v[94:97]
	v_mfma_f32_16x16x32_bf16 v[90:93], v[196:199], v[144:147], v[90:93]
	v_mfma_f32_16x16x32_bf16 v[78:81], v[212:215], v[136:139], v[78:81]
	v_mfma_f32_16x16x32_bf16 v[74:77], v[212:215], v[144:147], v[74:77]
	v_mfma_f32_16x16x32_bf16 v[126:129], v[184:187], v[140:143], v[126:129]
	v_mfma_f32_16x16x32_bf16 v[122:125], v[184:187], v[148:151], v[122:125]
	v_mfma_f32_16x16x32_bf16 v[110:113], v[192:195], v[140:143], v[110:113]
	v_mfma_f32_16x16x32_bf16 v[106:109], v[192:195], v[148:151], v[106:109]
	v_mfma_f32_16x16x32_bf16 v[94:97], v[208:211], v[140:143], v[94:97]
	v_mfma_f32_16x16x32_bf16 v[90:93], v[208:211], v[148:151], v[90:93]
	v_mfma_f32_16x16x32_bf16 v[78:81], v[216:219], v[140:143], v[78:81]
	v_mfma_f32_16x16x32_bf16 v[74:77], v[216:219], v[148:151], v[74:77]
	s_setprio 0
	s_setprio 1
	v_mfma_f32_16x16x32_bf16 v[118:121], v[180:183], v[152:155], v[118:121]
	v_mfma_f32_16x16x32_bf16 v[114:117], v[180:183], v[166:169], v[114:117]
	v_mfma_f32_16x16x32_bf16 v[102:105], v[188:191], v[152:155], v[102:105]
	v_mfma_f32_16x16x32_bf16 v[98:101], v[188:191], v[166:169], v[98:101]
	v_mfma_f32_16x16x32_bf16 v[86:89], v[196:199], v[152:155], v[86:89]
	v_mfma_f32_16x16x32_bf16 v[82:85], v[196:199], v[166:169], v[82:85]
	v_mfma_f32_16x16x32_bf16 v[70:73], v[212:215], v[152:155], v[70:73]
	v_mfma_f32_16x16x32_bf16 v[66:69], v[212:215], v[166:169], v[66:69]
	v_mfma_f32_16x16x32_bf16 v[118:121], v[184:187], v[162:165], v[118:121]
	v_mfma_f32_16x16x32_bf16 v[114:117], v[184:187], v[176:179], v[114:117]
	v_mfma_f32_16x16x32_bf16 v[102:105], v[192:195], v[162:165], v[102:105]
	v_mfma_f32_16x16x32_bf16 v[98:101], v[192:195], v[176:179], v[98:101]
	v_mfma_f32_16x16x32_bf16 v[86:89], v[208:211], v[162:165], v[86:89]
	v_mfma_f32_16x16x32_bf16 v[82:85], v[208:211], v[176:179], v[82:85]
	v_mfma_f32_16x16x32_bf16 v[70:73], v[216:219], v[162:165], v[70:73]
	v_mfma_f32_16x16x32_bf16 v[66:69], v[216:219], v[176:179], v[66:69]
	s_setprio 0
	s_barrier
; #define PG8_STAGE(bufoff, gbase, voff) do { _Pragma("unroll") for (int _i = 0; _i < 2; ++_i) \
;         __builtin_amdgcn_global_load_lds((const unsigned*)((const char*)(gbase) + (voff)[_i]), (PG8_LAS unsigned*)(lds + (bufoff) + ldsw + _i * 8192), 16, 0, 0); } while (0)
; #define PG8_LDA(dst, b, h) do { _Pragma("unroll") for (int m = 0; m < 4; ++m) _Pragma("unroll") for (int k = 0; k < 2; ++k) dst[m][k] = *(const PG8_LAS bf16x8*)(lds + PG8_SA(b, h) + aoff + m * 2048 + k * 1024); } while (0)
; #define PG8_LDB(dst, b, h) do { _Pragma("unroll") for (int n = 0; n < 2; ++n) _Pragma("unroll") for (int k = 0; k < 2; ++k) dst[n][k] = *(const PG8_LAS bf16x8*)(lds + PG8_SB(b, h) + boff + n * 2048 + k * 1024); } while (0)
; #define PG8_MMA(ai, bj, At, Bt) do { __builtin_amdgcn_s_setprio(1); _Pragma("unroll") for (int m = 0; m < 4; ++m) _Pragma("unroll") for (int n = 0; n < 2; ++n) _Pragma("unroll") for (int k = 0; k < 2; ++k) \
;         acc[ai][bj][m][n] = __builtin_amdgcn_mfma_f32_16x16x32_bf16(Bt[n][k], At[m][k], acc[ai][bj][m][n], 0, 0, 0); __builtin_amdgcn_s_setprio(0); } while (0)
; #define PG8_WAIT_V(n) asm volatile("s_waitcnt vmcnt(" #n ")" ::: "memory")
; #define PG8_WAIT_L(n) asm volatile("s_waitcnt lgkmcnt(" #n ")" ::: "memory")
; #define PG8_BAR __builtin_amdgcn_s_barrier()
; #define PG8_SCHED __builtin_amdgcn_sched_barrier(0)
; template <class Epi, class Sched, bool ALIGN_EPI = false, bool SP2 = false>
; __device__ __forceinline__ void gemm_phase(PG8_LAS unsigned char* lds, const Gemm g, const Sched& S, const Epi& E, int wave_s) {
;     ...
;             PG8_LDB(B0, 1, 0); PG8_LDB(B1, 1, 1); PG8_SCHED; PG8_LDA(At, 1, 0); PG8_STAGE(PG8_SA(0, 1), a2 + hstepA, voffA);
;             PG8_WAIT_V(8); PG8_WAIT_L(0); PG8_BAR; PG8_MMA(0, 0, At, B0); PG8_MMA(0, 1, At, B1); PG8_BAR; PG8_SCHED;
;             PG8_LDA(At, 1, 1); PG8_STAGE(PG8_SB(1, 0), b3, voffB); PG8_STAGE(PG8_SB(1, 1), b3 + hstepB, voffB); PG8_STAGE(PG8_SA(1, 0), a3, voffA);
;             PG8_WAIT_V(8); PG8_WAIT_L(0); PG8_BAR; PG8_MMA(1, 0, At, B0); PG8_MMA(1, 1, At, B1); PG8_BAR; PG8_SCHED;
	s_add_i32 s16, s34, s37
	v_lshl_add_u64 v[156:157], v[156:157], 0, s[30:31]
	s_mov_b32 m0, s16
	ds_read_b128 v[180:183], v161 offset:49152
	ds_read_b128 v[184:187], v161 offset:50176
	ds_read_b128 v[188:191], v161 offset:51200
	ds_read_b128 v[192:195], v161 offset:52224
	ds_read_b128 v[196:199], v161 offset:53248
	ds_read_b128 v[208:211], v161 offset:54272
	ds_read_b128 v[212:215], v161 offset:55296
	ds_read_b128 v[216:219], v161 offset:56320
	global_load_lds_dwordx4 v[156:157], off
	s_add_i32 m0, s16, 0x2000
	s_add_u32 s16, s20, 0x160080
	v_lshl_add_u64 v[156:157], v[170:171], 0, s[30:31]
	s_addc_u32 s17, s21, 0
	s_add_i32 s20, s35, s37
	global_load_lds_dwordx4 v[156:157], off
	v_lshl_add_u64 v[156:157], s[16:17], 0, v[0:1]
	s_mov_b32 m0, s20
	s_nop 0
	global_load_lds_dwordx4 v[156:157], off
	v_lshl_add_u64 v[156:157], s[16:17], 0, v[130:131]
	s_add_i32 m0, s20, 0x2000
	s_nop 0
	global_load_lds_dwordx4 v[156:157], off
	s_mov_b64 s[100:101], 0x8000
	v_lshl_add_u64 v[156:157], v[200:201], 0, s[100:101]
	s_mov_b32 m0, s48
	s_nop 0
	global_load_lds_dwordx4 v[156:157], off
	v_lshl_add_u64 v[156:157], v[220:221], 0, s[100:101]
	s_mov_b32 m0, s49
	s_nop 0
	global_load_lds_dwordx4 v[156:157], off
	s_waitcnt vmcnt(8)
	s_waitcnt lgkmcnt(0)
	s_barrier
	s_setprio 1
	s_waitcnt lgkmcnt(0)
	v_mfma_f32_16x16x32_bf16 v[62:65], v[180:183], v[136:139], v[62:65]
	v_mfma_f32_16x16x32_bf16 v[58:61], v[180:183], v[144:147], v[58:61]
	v_mfma_f32_16x16x32_bf16 v[46:49], v[188:191], v[136:139], v[46:49]
	v_mfma_f32_16x16x32_bf16 v[42:45], v[188:191], v[144:147], v[42:45]
	v_mfma_f32_16x16x32_bf16 v[30:33], v[196:199], v[136:139], v[30:33]
	v_mfma_f32_16x16x32_bf16 v[26:29], v[196:199], v[144:147], v[26:29]
	v_mfma_f32_16x16x32_bf16 v[14:17], v[212:215], v[136:139], v[14:17]
	v_mfma_f32_16x16x32_bf16 v[10:13], v[212:215], v[144:147], v[10:13]
	v_mfma_f32_16x16x32_bf16 v[62:65], v[184:187], v[140:143], v[62:65]
	v_mfma_f32_16x16x32_bf16 v[58:61], v[184:187], v[148:151], v[58:61]
	v_mfma_f32_16x16x32_bf16 v[46:49], v[192:195], v[140:143], v[46:49]
	v_mfma_f32_16x16x32_bf16 v[42:45], v[192:195], v[148:151], v[42:45]
	v_mfma_f32_16x16x32_bf16 v[30:33], v[208:211], v[140:143], v[30:33]
	v_mfma_f32_16x16x32_bf16 v[26:29], v[208:211], v[148:151], v[26:29]
	v_mfma_f32_16x16x32_bf16 v[14:17], v[216:219], v[140:143], v[14:17]
	v_mfma_f32_16x16x32_bf16 v[10:13], v[216:219], v[148:151], v[10:13]
	s_setprio 0
	s_setprio 1
	v_mfma_f32_16x16x32_bf16 v[54:57], v[180:183], v[152:155], v[54:57]
	v_mfma_f32_16x16x32_bf16 v[50:53], v[180:183], v[166:169], v[50:53]
	v_mfma_f32_16x16x32_bf16 v[38:41], v[188:191], v[152:155], v[38:41]
	v_mfma_f32_16x16x32_bf16 v[34:37], v[188:191], v[166:169], v[34:37]
	v_mfma_f32_16x16x32_bf16 v[22:25], v[196:199], v[152:155], v[22:25]
	v_mfma_f32_16x16x32_bf16 v[18:21], v[196:199], v[166:169], v[18:21]
	v_mfma_f32_16x16x32_bf16 v[6:9], v[212:215], v[152:155], v[6:9]
	v_mfma_f32_16x16x32_bf16 v[2:5], v[212:215], v[166:169], v[2:5]
	v_mfma_f32_16x16x32_bf16 v[54:57], v[184:187], v[162:165], v[54:57]
	v_mfma_f32_16x16x32_bf16 v[50:53], v[184:187], v[176:179], v[50:53]
	v_mfma_f32_16x16x32_bf16 v[38:41], v[192:195], v[162:165], v[38:41]
	v_mfma_f32_16x16x32_bf16 v[34:37], v[192:195], v[176:179], v[34:37]
	v_mfma_f32_16x16x32_bf16 v[22:25], v[208:211], v[162:165], v[22:25]
	v_mfma_f32_16x16x32_bf16 v[18:21], v[208:211], v[176:179], v[18:21]
	v_mfma_f32_16x16x32_bf16 v[6:9], v[216:219], v[162:165], v[6:9]
	v_mfma_f32_16x16x32_bf16 v[2:5], v[216:219], v[176:179], v[2:5]
	s_setprio 0
	s_barrier
	s_add_i32 s41, s41, 2
	s_add_u32 s27, s27, 0x100
	s_addc_u32 s40, s40, 0
	s_cmpk_gt_u32 s41, 0x55
	s_mov_b64 s[16:17], s[18:19]
	s_cbranch_scc0 .LBB0_358
	s_and_b64 vcc, exec, s[10:11]
	s_cbranch_vccz .LBB0_361
	s_barrier

; __device__ __forceinline__ unsigned cvt_pk_bf16(float lo, float hi) { const pk_f2_t v = {lo, hi}; return __builtin_bit_cast(unsigned, __builtin_convertvector(v, pk_bf2_t)); }
; __device__ __forceinline__ float silu_f(float g) { return g * __builtin_amdgcn_rcpf(1.0f + __builtin_amdgcn_exp2f(-1.4426950408889634f * g)); }
;     __device__ __forceinline__ void operator()(const pg8::f32x4 (&acc)[2][2][4][2], const pg8::Unit& u, int wr, int wc, int fr, int fq) const {
;         const int row0 = u.pm * 256 + wr * 64 + fr, col0 = u.pn * 128 + wc * 32 + 8 * fq;
;         bf16* base = O + (size_t)row0 * FF + col0;
; #pragma unroll
;         for (int ai = 0; ai < 2; ++ai)
; #pragma unroll
;             for (int m = 0; m < 4; ++m) {
;                 pg8::u32x4 w;
;                 { const pg8::f32x4 g = acc[ai][0][m][0], uu = acc[ai][1][m][0];
;                   w.x = pg8::cvt_pk_bf16(silu_f(g[0]) * uu[0], silu_f(g[1]) * uu[1]); w.y = pg8::cvt_pk_bf16(silu_f(g[2]) * uu[2], silu_f(g[3]) * uu[3]); }
;                 { const pg8::f32x4 g = acc[ai][0][m][1], uu = acc[ai][1][m][1];
;                   w.z = pg8::cvt_pk_bf16(silu_f(g[0]) * uu[0], silu_f(g[1]) * uu[1]); w.w = pg8::cvt_pk_bf16(silu_f(g[2]) * uu[2], silu_f(g[3]) * uu[3]); }
;                 *(pg8::u32x4*)(base + (size_t)(ai * 128 + m * 16) * FF) = w;
;                 asm volatile("" ::: "memory");
;             }
.LBB0_1800:
	s_lshl_b32 s100, s26, 1
	v_lshrrev_b32_e32 v141, 6, v144
	v_add_u32_e32 v141, s100, v141
	v_lshlrev_b32_e32 v141, 15, v141
	v_and_b32_e32 v140, 63, v144
	v_lshlrev_b32_e32 v140, 1, v140
	v_lshl_add_u32 v140, v142, 7, v140
	v_add_u32_e32 v140, v140, v141
	s_mul_i32 s100, s27, 0x2c0000
	s_add_u32 s100, s6, s100
	s_addc_u32 s101, s7, 0
	v_mov_b32_e32 v141, 0
	v_lshl_add_u64 v[140:141], s[100:101], 0, v[140:141]
	s_mov_b64 s[18:19], -1
	v_mul_f32_e32 v150, 0xbfb8aa3b, v126
	v_mul_f32_e32 v151, 0xbfb8aa3b, v127
	v_mul_f32_e32 v152, 0xbfb8aa3b, v128
	v_mul_f32_e32 v153, 0xbfb8aa3b, v129
	v_mul_f32_e32 v154, 0xbfb8aa3b, v118
	v_mul_f32_e32 v155, 0xbfb8aa3b, v119
	v_mul_f32_e32 v156, 0xbfb8aa3b, v120
	v_mul_f32_e32 v157, 0xbfb8aa3b, v121
	v_exp_f32_e32 v150, v150
	v_exp_f32_e32 v151, v151
	v_exp_f32_e32 v152, v152
	v_exp_f32_e32 v153, v153
	v_exp_f32_e32 v154, v154
	v_exp_f32_e32 v155, v155
	v_exp_f32_e32 v156, v156
	v_exp_f32_e32 v157, v157
	v_add_f32_e32 v150, 1.0, v150
	v_add_f32_e32 v151, 1.0, v151
	v_add_f32_e32 v152, 1.0, v152
	v_add_f32_e32 v153, 1.0, v153
	v_add_f32_e32 v154, 1.0, v154
	v_add_f32_e32 v155, 1.0, v155
	v_add_f32_e32 v156, 1.0, v156
	v_add_f32_e32 v157, 1.0, v157
	v_rcp_f32_e32 v150, v150
	v_rcp_f32_e32 v151, v151
	v_rcp_f32_e32 v152, v152
	v_rcp_f32_e32 v153, v153
	v_rcp_f32_e32 v154, v154
	v_rcp_f32_e32 v155, v155
	v_rcp_f32_e32 v156, v156
	v_rcp_f32_e32 v157, v157
	v_mul_f32_e32 v150, v126, v150
	v_mul_f32_e32 v151, v127, v151
	v_mul_f32_e32 v152, v128, v152
	v_mul_f32_e32 v153, v129, v153
	v_mul_f32_e32 v154, v118, v154
	v_mul_f32_e32 v155, v119, v155
	v_mul_f32_e32 v156, v120, v156
	v_mul_f32_e32 v157, v121, v157
	v_mul_f32_e32 v122, v150, v122
	v_mul_f32_e32 v123, v151, v123
	v_mul_f32_e32 v124, v152, v124
	v_mul_f32_e32 v125, v153, v125
	v_mul_f32_e32 v114, v154, v114
	v_mul_f32_e32 v115, v155, v115
	v_mul_f32_e32 v116, v156, v116
	v_mul_f32_e32 v117, v157, v117
	v_cvt_pk_bf16_f32 v122, v122, v123
	v_cvt_pk_bf16_f32 v123, v124, v125
	v_cvt_pk_bf16_f32 v124, v114, v115
	v_cvt_pk_bf16_f32 v125, v116, v117
	flat_store_dwordx4 v[140:141], v[122:125]
	v_mul_f32_e32 v158, 0xbfb8aa3b, v110
	v_mul_f32_e32 v159, 0xbfb8aa3b, v111
	v_mul_f32_e32 v160, 0xbfb8aa3b, v112
	v_mul_f32_e32 v161, 0xbfb8aa3b, v113
	v_mul_f32_e32 v162, 0xbfb8aa3b, v102
	v_mul_f32_e32 v163, 0xbfb8aa3b, v103
	v_mul_f32_e32 v164, 0xbfb8aa3b, v104
	v_mul_f32_e32 v165, 0xbfb8aa3b, v105
	v_exp_f32_e32 v158, v158
	v_exp_f32_e32 v159, v159
	v_exp_f32_e32 v160, v160
	v_exp_f32_e32 v161, v161
	v_exp_f32_e32 v162, v162
	v_exp_f32_e32 v163, v163
	v_exp_f32_e32 v164, v164
	v_exp_f32_e32 v165, v165
	v_add_co_u32_e32 v166, vcc, 0x800, v140
	v_add_f32_e32 v158, 1.0, v158
	v_add_f32_e32 v159, 1.0, v159
	v_add_f32_e32 v160, 1.0, v160
	v_add_f32_e32 v161, 1.0, v161
	v_add_f32_e32 v162, 1.0, v162
	v_add_f32_e32 v163, 1.0, v163
	v_add_f32_e32 v164, 1.0, v164
	v_add_f32_e32 v165, 1.0, v165
	v_addc_co_u32_e32 v167, vcc, 0, v141, vcc
	v_rcp_f32_e32 v158, v158
	v_rcp_f32_e32 v159, v159
	v_rcp_f32_e32 v160, v160
	v_rcp_f32_e32 v161, v161
	v_rcp_f32_e32 v162, v162
	v_rcp_f32_e32 v163, v163
	v_rcp_f32_e32 v164, v164
	v_rcp_f32_e32 v165, v165
	v_mul_f32_e32 v158, v110, v158
	v_mul_f32_e32 v159, v111, v159
	v_mul_f32_e32 v160, v112, v160
	v_mul_f32_e32 v161, v113, v161
	v_mul_f32_e32 v162, v102, v162
	v_mul_f32_e32 v163, v103, v163
	v_mul_f32_e32 v164, v104, v164
	v_mul_f32_e32 v165, v105, v165
	v_mul_f32_e32 v106, v158, v106
	v_mul_f32_e32 v107, v159, v107
	v_mul_f32_e32 v108, v160, v108
	v_mul_f32_e32 v109, v161, v109
	v_mul_f32_e32 v98, v162, v98
	v_mul_f32_e32 v99, v163, v99
	v_mul_f32_e32 v100, v164, v100
	v_mul_f32_e32 v101, v165, v101
	v_cvt_pk_bf16_f32 v106, v106, v107
	v_cvt_pk_bf16_f32 v107, v108, v109
	v_cvt_pk_bf16_f32 v108, v98, v99
	v_cvt_pk_bf16_f32 v109, v100, v101
	flat_store_dwordx4 v[166:167], v[106:109]
	v_mul_f32_e32 v150, 0xbfb8aa3b, v94
	v_mul_f32_e32 v151, 0xbfb8aa3b, v95
	v_mul_f32_e32 v152, 0xbfb8aa3b, v96
	v_mul_f32_e32 v153, 0xbfb8aa3b, v97
	v_mul_f32_e32 v154, 0xbfb8aa3b, v86
	v_mul_f32_e32 v155, 0xbfb8aa3b, v87
	v_mul_f32_e32 v156, 0xbfb8aa3b, v88
	v_mul_f32_e32 v157, 0xbfb8aa3b, v89
	v_exp_f32_e32 v150, v150
	v_exp_f32_e32 v151, v151
	v_exp_f32_e32 v152, v152
	v_exp_f32_e32 v153, v153
	v_exp_f32_e32 v154, v154
	v_exp_f32_e32 v155, v155
	v_exp_f32_e32 v156, v156
	v_exp_f32_e32 v157, v157
	v_add_co_u32_e32 v148, vcc, 0x1000, v140
	v_add_f32_e32 v150, 1.0, v150
	v_add_f32_e32 v151, 1.0, v151
	v_add_f32_e32 v152, 1.0, v152
	v_add_f32_e32 v153, 1.0, v153
	v_add_f32_e32 v154, 1.0, v154
	v_add_f32_e32 v155, 1.0, v155
	v_add_f32_e32 v156, 1.0, v156
	v_add_f32_e32 v157, 1.0, v157
	v_addc_co_u32_e32 v149, vcc, 0, v141, vcc
	v_rcp_f32_e32 v150, v150
	v_rcp_f32_e32 v151, v151
	v_rcp_f32_e32 v152, v152
	v_rcp_f32_e32 v153, v153
	v_rcp_f32_e32 v154, v154
	v_rcp_f32_e32 v155, v155
	v_rcp_f32_e32 v156, v156
	v_rcp_f32_e32 v157, v157
	v_mul_f32_e32 v150, v94, v150
	v_mul_f32_e32 v151, v95, v151
	v_mul_f32_e32 v152, v96, v152
	v_mul_f32_e32 v153, v97, v153
	v_mul_f32_e32 v154, v86, v154
	v_mul_f32_e32 v155, v87, v155
	v_mul_f32_e32 v156, v88, v156
	v_mul_f32_e32 v157, v89, v157
	v_mul_f32_e32 v90, v150, v90
	v_mul_f32_e32 v91, v151, v91
	v_mul_f32_e32 v92, v152, v92
	v_mul_f32_e32 v93, v153, v93
	v_mul_f32_e32 v82, v154, v82
	v_mul_f32_e32 v83, v155, v83
	v_mul_f32_e32 v84, v156, v84
	v_mul_f32_e32 v85, v157, v85
	v_cvt_pk_bf16_f32 v90, v90, v91
	v_cvt_pk_bf16_f32 v91, v92, v93
	v_cvt_pk_bf16_f32 v92, v82, v83
	v_cvt_pk_bf16_f32 v93, v84, v85
	flat_store_dwordx4 v[148:149], v[90:93]
	v_mul_f32_e32 v158, 0xbfb8aa3b, v78
	v_mul_f32_e32 v159, 0xbfb8aa3b, v79
; __device__ __forceinline__ unsigned cvt_pk_bf16(float lo, float hi) { const pk_f2_t v = {lo, hi}; return __builtin_bit_cast(unsigned, __builtin_convertvector(v, pk_bf2_t)); }
; __device__ __forceinline__ float silu_f(float g) { return g * __builtin_amdgcn_rcpf(1.0f + __builtin_amdgcn_exp2f(-1.4426950408889634f * g)); }
;     __device__ __forceinline__ void operator()(const pg8::f32x4 (&acc)[2][2][4][2], const pg8::Unit& u, int wr, int wc, int fr, int fq) const {
;     ...
;             for (int m = 0; m < 4; ++m) {
;                 pg8::u32x4 w;
;                 { const pg8::f32x4 g = acc[ai][0][m][0], uu = acc[ai][1][m][0];
;                   w.x = pg8::cvt_pk_bf16(silu_f(g[0]) * uu[0], silu_f(g[1]) * uu[1]); w.y = pg8::cvt_pk_bf16(silu_f(g[2]) * uu[2], silu_f(g[3]) * uu[3]); }
;                 { const pg8::f32x4 g = acc[ai][0][m][1], uu = acc[ai][1][m][1];
;                   w.z = pg8::cvt_pk_bf16(silu_f(g[0]) * uu[0], silu_f(g[1]) * uu[1]); w.w = pg8::cvt_pk_bf16(silu_f(g[2]) * uu[2], silu_f(g[3]) * uu[3]); }
;                 *(pg8::u32x4*)(base + (size_t)(ai * 128 + m * 16) * FF) = w;
;                 asm volatile("" ::: "memory");
;             }
	v_mul_f32_e32 v160, 0xbfb8aa3b, v80
	v_mul_f32_e32 v161, 0xbfb8aa3b, v81
	v_mul_f32_e32 v162, 0xbfb8aa3b, v70
	v_mul_f32_e32 v163, 0xbfb8aa3b, v71
	v_mul_f32_e32 v164, 0xbfb8aa3b, v72
	v_mul_f32_e32 v165, 0xbfb8aa3b, v73
	v_exp_f32_e32 v158, v158
	v_exp_f32_e32 v159, v159
	v_exp_f32_e32 v160, v160
	v_exp_f32_e32 v161, v161
	v_exp_f32_e32 v162, v162
	v_exp_f32_e32 v163, v163
	v_exp_f32_e32 v164, v164
	v_exp_f32_e32 v165, v165
	v_add_co_u32_e32 v166, vcc, 0x1800, v140
	v_add_f32_e32 v158, 1.0, v158
	v_add_f32_e32 v159, 1.0, v159
	v_add_f32_e32 v160, 1.0, v160
	v_add_f32_e32 v161, 1.0, v161
	v_add_f32_e32 v162, 1.0, v162
	v_add_f32_e32 v163, 1.0, v163
	v_add_f32_e32 v164, 1.0, v164
	v_add_f32_e32 v165, 1.0, v165
	v_addc_co_u32_e32 v167, vcc, 0, v141, vcc
	v_rcp_f32_e32 v158, v158
	v_rcp_f32_e32 v159, v159
	v_rcp_f32_e32 v160, v160
	v_rcp_f32_e32 v161, v161
	v_rcp_f32_e32 v162, v162
	v_rcp_f32_e32 v163, v163
	v_rcp_f32_e32 v164, v164
	v_rcp_f32_e32 v165, v165
	v_mul_f32_e32 v158, v78, v158
	v_mul_f32_e32 v159, v79, v159
	v_mul_f32_e32 v160, v80, v160
	v_mul_f32_e32 v161, v81, v161
	v_mul_f32_e32 v162, v70, v162
	v_mul_f32_e32 v163, v71, v163
	v_mul_f32_e32 v164, v72, v164
	v_mul_f32_e32 v165, v73, v165
	v_mul_f32_e32 v74, v158, v74
	v_mul_f32_e32 v75, v159, v75
	v_mul_f32_e32 v76, v160, v76
	v_mul_f32_e32 v77, v161, v77
	v_mul_f32_e32 v66, v162, v66
	v_mul_f32_e32 v67, v163, v67
	v_mul_f32_e32 v68, v164, v68
	v_mul_f32_e32 v69, v165, v69
	v_cvt_pk_bf16_f32 v74, v74, v75
	v_cvt_pk_bf16_f32 v75, v76, v77
	v_cvt_pk_bf16_f32 v76, v66, v67
	v_cvt_pk_bf16_f32 v77, v68, v69
	flat_store_dwordx4 v[166:167], v[74:77]
	v_mul_f32_e32 v150, 0xbfb8aa3b, v62
	v_mul_f32_e32 v151, 0xbfb8aa3b, v63
	v_mul_f32_e32 v152, 0xbfb8aa3b, v64
	v_mul_f32_e32 v153, 0xbfb8aa3b, v65
	v_mul_f32_e32 v154, 0xbfb8aa3b, v54
	v_mul_f32_e32 v155, 0xbfb8aa3b, v55
	v_mul_f32_e32 v156, 0xbfb8aa3b, v56
	v_mul_f32_e32 v157, 0xbfb8aa3b, v57
	v_exp_f32_e32 v150, v150
	v_exp_f32_e32 v151, v151
	v_exp_f32_e32 v152, v152
	v_exp_f32_e32 v153, v153
	v_exp_f32_e32 v154, v154
	v_exp_f32_e32 v155, v155
	v_exp_f32_e32 v156, v156
	v_exp_f32_e32 v157, v157
	v_add_co_u32_e32 v148, vcc, 0x4000, v140
	v_add_f32_e32 v150, 1.0, v150
	v_add_f32_e32 v151, 1.0, v151
	v_add_f32_e32 v152, 1.0, v152
	v_add_f32_e32 v153, 1.0, v153
	v_add_f32_e32 v154, 1.0, v154
	v_add_f32_e32 v155, 1.0, v155
	v_add_f32_e32 v156, 1.0, v156
	v_add_f32_e32 v157, 1.0, v157
	v_addc_co_u32_e32 v149, vcc, 0, v141, vcc
	v_rcp_f32_e32 v150, v150
	v_rcp_f32_e32 v151, v151
	v_rcp_f32_e32 v152, v152
	v_rcp_f32_e32 v153, v153
	v_rcp_f32_e32 v154, v154
	v_rcp_f32_e32 v155, v155
	v_rcp_f32_e32 v156, v156
	v_rcp_f32_e32 v157, v157
	v_mul_f32_e32 v150, v62, v150
	v_mul_f32_e32 v151, v63, v151
	v_mul_f32_e32 v152, v64, v152
	v_mul_f32_e32 v153, v65, v153
	v_mul_f32_e32 v154, v54, v154
	v_mul_f32_e32 v155, v55, v155
	v_mul_f32_e32 v156, v56, v156
	v_mul_f32_e32 v157, v57, v157
	v_mul_f32_e32 v58, v150, v58
	v_mul_f32_e32 v59, v151, v59
	v_mul_f32_e32 v60, v152, v60
	v_mul_f32_e32 v61, v153, v61
	v_mul_f32_e32 v50, v154, v50
	v_mul_f32_e32 v51, v155, v51
	v_mul_f32_e32 v52, v156, v52
	v_mul_f32_e32 v53, v157, v53
	v_cvt_pk_bf16_f32 v58, v58, v59
	v_cvt_pk_bf16_f32 v59, v60, v61
	v_cvt_pk_bf16_f32 v60, v50, v51
	v_cvt_pk_bf16_f32 v61, v52, v53
	flat_store_dwordx4 v[148:149], v[58:61]
	v_mul_f32_e32 v158, 0xbfb8aa3b, v46
	v_mul_f32_e32 v159, 0xbfb8aa3b, v47
	v_mul_f32_e32 v160, 0xbfb8aa3b, v48
	v_mul_f32_e32 v161, 0xbfb8aa3b, v49
	v_mul_f32_e32 v162, 0xbfb8aa3b, v38
	v_mul_f32_e32 v163, 0xbfb8aa3b, v39
	v_mul_f32_e32 v164, 0xbfb8aa3b, v40
	v_mul_f32_e32 v165, 0xbfb8aa3b, v41
	v_exp_f32_e32 v158, v158
	v_exp_f32_e32 v159, v159
	v_exp_f32_e32 v160, v160
	v_exp_f32_e32 v161, v161
	v_exp_f32_e32 v162, v162
	v_exp_f32_e32 v163, v163
	v_exp_f32_e32 v164, v164
	v_exp_f32_e32 v165, v165
	v_add_co_u32_e32 v166, vcc, 0x4800, v140
	v_add_f32_e32 v158, 1.0, v158
	v_add_f32_e32 v159, 1.0, v159
	v_add_f32_e32 v160, 1.0, v160
	v_add_f32_e32 v161, 1.0, v161
	v_add_f32_e32 v162, 1.0, v162
	v_add_f32_e32 v163, 1.0, v163
	v_add_f32_e32 v164, 1.0, v164
	v_add_f32_e32 v165, 1.0, v165
	v_addc_co_u32_e32 v167, vcc, 0, v141, vcc
	v_rcp_f32_e32 v158, v158
	v_rcp_f32_e32 v159, v159
	v_rcp_f32_e32 v160, v160
	v_rcp_f32_e32 v161, v161
	v_rcp_f32_e32 v162, v162
; __device__ __forceinline__ unsigned cvt_pk_bf16(float lo, float hi) { const pk_f2_t v = {lo, hi}; return __builtin_bit_cast(unsigned, __builtin_convertvector(v, pk_bf2_t)); }
; __device__ __forceinline__ float silu_f(float g) { return g * __builtin_amdgcn_rcpf(1.0f + __builtin_amdgcn_exp2f(-1.4426950408889634f * g)); }
;     __device__ __forceinline__ void operator()(const pg8::f32x4 (&acc)[2][2][4][2], const pg8::Unit& u, int wr, int wc, int fr, int fq) const {
;     ...
;             for (int m = 0; m < 4; ++m) {
;                 pg8::u32x4 w;
;                 { const pg8::f32x4 g = acc[ai][0][m][0], uu = acc[ai][1][m][0];
;                   w.x = pg8::cvt_pk_bf16(silu_f(g[0]) * uu[0], silu_f(g[1]) * uu[1]); w.y = pg8::cvt_pk_bf16(silu_f(g[2]) * uu[2], silu_f(g[3]) * uu[3]); }
;                 { const pg8::f32x4 g = acc[ai][0][m][1], uu = acc[ai][1][m][1];
;                   w.z = pg8::cvt_pk_bf16(silu_f(g[0]) * uu[0], silu_f(g[1]) * uu[1]); w.w = pg8::cvt_pk_bf16(silu_f(g[2]) * uu[2], silu_f(g[3]) * uu[3]); }
;                 *(pg8::u32x4*)(base + (size_t)(ai * 128 + m * 16) * FF) = w;
;                 asm volatile("" ::: "memory");
;             }
	v_rcp_f32_e32 v163, v163
	v_rcp_f32_e32 v164, v164
	v_rcp_f32_e32 v165, v165
	v_mul_f32_e32 v158, v46, v158
	v_mul_f32_e32 v159, v47, v159
	v_mul_f32_e32 v160, v48, v160
	v_mul_f32_e32 v161, v49, v161
	v_mul_f32_e32 v162, v38, v162
	v_mul_f32_e32 v163, v39, v163
	v_mul_f32_e32 v164, v40, v164
	v_mul_f32_e32 v165, v41, v165
	v_mul_f32_e32 v42, v158, v42
	v_mul_f32_e32 v43, v159, v43
	v_mul_f32_e32 v44, v160, v44
	v_mul_f32_e32 v45, v161, v45
	v_mul_f32_e32 v34, v162, v34
	v_mul_f32_e32 v35, v163, v35
	v_mul_f32_e32 v36, v164, v36
	v_mul_f32_e32 v37, v165, v37
	v_cvt_pk_bf16_f32 v42, v42, v43
	v_cvt_pk_bf16_f32 v43, v44, v45
	v_cvt_pk_bf16_f32 v44, v34, v35
	v_cvt_pk_bf16_f32 v45, v36, v37
	flat_store_dwordx4 v[166:167], v[42:45]
	v_mul_f32_e32 v150, 0xbfb8aa3b, v30
	v_mul_f32_e32 v151, 0xbfb8aa3b, v31
	v_mul_f32_e32 v152, 0xbfb8aa3b, v32
	v_mul_f32_e32 v153, 0xbfb8aa3b, v33
	v_mul_f32_e32 v154, 0xbfb8aa3b, v22
	v_mul_f32_e32 v155, 0xbfb8aa3b, v23
	v_mul_f32_e32 v156, 0xbfb8aa3b, v24
	v_mul_f32_e32 v157, 0xbfb8aa3b, v25
	v_exp_f32_e32 v150, v150
	v_exp_f32_e32 v151, v151
	v_exp_f32_e32 v152, v152
	v_exp_f32_e32 v153, v153
	v_exp_f32_e32 v154, v154
	v_exp_f32_e32 v155, v155
	v_exp_f32_e32 v156, v156
	v_exp_f32_e32 v157, v157
	v_add_co_u32_e32 v148, vcc, 0x5000, v140
	v_add_f32_e32 v150, 1.0, v150
	v_add_f32_e32 v151, 1.0, v151
	v_add_f32_e32 v152, 1.0, v152
	v_add_f32_e32 v153, 1.0, v153
	v_add_f32_e32 v154, 1.0, v154
	v_add_f32_e32 v155, 1.0, v155
	v_add_f32_e32 v156, 1.0, v156
	v_add_f32_e32 v157, 1.0, v157
	v_addc_co_u32_e32 v149, vcc, 0, v141, vcc
	v_rcp_f32_e32 v150, v150
	v_rcp_f32_e32 v151, v151
	v_rcp_f32_e32 v152, v152
	v_rcp_f32_e32 v153, v153
	v_rcp_f32_e32 v154, v154
	v_rcp_f32_e32 v155, v155
	v_rcp_f32_e32 v156, v156
	v_rcp_f32_e32 v157, v157
	v_mul_f32_e32 v150, v30, v150
	v_mul_f32_e32 v151, v31, v151
	v_mul_f32_e32 v152, v32, v152
	v_mul_f32_e32 v153, v33, v153
	v_mul_f32_e32 v154, v22, v154
	v_mul_f32_e32 v155, v23, v155
	v_mul_f32_e32 v156, v24, v156
	v_mul_f32_e32 v157, v25, v157
	v_mul_f32_e32 v26, v150, v26
	v_mul_f32_e32 v27, v151, v27
	v_mul_f32_e32 v28, v152, v28
	v_mul_f32_e32 v29, v153, v29
	v_mul_f32_e32 v18, v154, v18
	v_mul_f32_e32 v19, v155, v19
	v_mul_f32_e32 v20, v156, v20
	v_mul_f32_e32 v21, v157, v21
	v_cvt_pk_bf16_f32 v26, v26, v27
	v_cvt_pk_bf16_f32 v27, v28, v29
	v_cvt_pk_bf16_f32 v28, v18, v19
	v_cvt_pk_bf16_f32 v29, v20, v21
	flat_store_dwordx4 v[148:149], v[26:29]
	v_mul_f32_e32 v158, 0xbfb8aa3b, v14
	v_mul_f32_e32 v159, 0xbfb8aa3b, v15
	v_mul_f32_e32 v160, 0xbfb8aa3b, v16
	v_mul_f32_e32 v161, 0xbfb8aa3b, v17
	v_mul_f32_e32 v162, 0xbfb8aa3b, v6
	v_mul_f32_e32 v163, 0xbfb8aa3b, v7
	v_mul_f32_e32 v164, 0xbfb8aa3b, v8
	v_mul_f32_e32 v165, 0xbfb8aa3b, v9
	v_exp_f32_e32 v158, v158
	v_exp_f32_e32 v159, v159
	v_exp_f32_e32 v160, v160
	v_exp_f32_e32 v161, v161
	v_exp_f32_e32 v162, v162
	v_exp_f32_e32 v163, v163
	v_exp_f32_e32 v164, v164
	v_exp_f32_e32 v165, v165
	v_add_co_u32_e32 v166, vcc, 0x5800, v140
	v_add_f32_e32 v158, 1.0, v158
	v_add_f32_e32 v159, 1.0, v159
	v_add_f32_e32 v160, 1.0, v160
	v_add_f32_e32 v161, 1.0, v161
	v_add_f32_e32 v162, 1.0, v162
	v_add_f32_e32 v163, 1.0, v163
	v_add_f32_e32 v164, 1.0, v164
	v_add_f32_e32 v165, 1.0, v165
	v_addc_co_u32_e32 v167, vcc, 0, v141, vcc
	v_rcp_f32_e32 v158, v158
	v_rcp_f32_e32 v159, v159
	v_rcp_f32_e32 v160, v160
	v_rcp_f32_e32 v161, v161
	v_rcp_f32_e32 v162, v162
	v_rcp_f32_e32 v163, v163
	v_rcp_f32_e32 v164, v164
	v_rcp_f32_e32 v165, v165
	v_mul_f32_e32 v158, v14, v158
	v_mul_f32_e32 v159, v15, v159
	v_mul_f32_e32 v160, v16, v160
	v_mul_f32_e32 v161, v17, v161
	v_mul_f32_e32 v162, v6, v162
	v_mul_f32_e32 v163, v7, v163
	v_mul_f32_e32 v164, v8, v164
	v_mul_f32_e32 v165, v9, v165
	v_mul_f32_e32 v10, v158, v10
	v_mul_f32_e32 v11, v159, v11
	v_mul_f32_e32 v12, v160, v12
	v_mul_f32_e32 v13, v161, v13
	v_mul_f32_e32 v2, v162, v2
	v_mul_f32_e32 v3, v163, v3
	v_mul_f32_e32 v4, v164, v4
	v_mul_f32_e32 v5, v165, v5
	v_cvt_pk_bf16_f32 v10, v10, v11
	v_cvt_pk_bf16_f32 v11, v12, v13
	v_cvt_pk_bf16_f32 v12, v2, v3
	v_cvt_pk_bf16_f32 v13, v4, v5
	flat_store_dwordx4 v[166:167], v[10:13]
	s_andn2_b64 vcc, exec, s[36:37]
	s_cbranch_vccnz .LBB0_1793
	s_andn2_b64 vcc, exec, s[0:1]
	s_cbranch_vccnz .LBB0_1792
	s_barrier
	s_branch .LBB0_1792

; #define PG8_STAGE(bufoff, gbase, voff) do { _Pragma("unroll") for (int _i = 0; _i < 2; ++_i) \
;         __builtin_amdgcn_global_load_lds((const unsigned*)((const char*)(gbase) + (voff)[_i]), (PG8_LAS unsigned*)(lds + (bufoff) + ldsw + _i * 8192), 16, 0, 0); } while (0)
; #define PG8_BAR __builtin_amdgcn_s_barrier()
; template <class Epi, class Sched, bool ALIGN_EPI = false, bool SP2 = false>
; __device__ __forceinline__ void gemm_phase(PG8_LAS unsigned char* lds, const Gemm g, const Sched& S, const Epi& E, int wave_s) {
;     ...
;     const int tid = tid_, wid = __builtin_amdgcn_readfirstlane(tid >> 6), lane = tid & 63, wr = wid >> 2, wc = wid & 3, fr = lane & 15, fq = lane >> 4;
;     const int K = g.K, nt = K / BK;
;     unsigned voffA[2], voffB[2];
; #pragma unroll
;     for (int i = 0; i < 2; ++i) { int R, C; stage_rc(tid * 16 + i * 8192, R, C); const int Rb = Epi::PERM ? ((R & ~31) + perm32(R & 31)) : R;
;         voffA[i] = (unsigned)(R * g.lda + C) * 2u; voffB[i] = (unsigned)(Rb * g.ldb + C) * 2u; }
;     const size_t kstep = (size_t)(BK * 2);
;     const size_t hstepA = (size_t)HALF * g.lda * 2, hstepB = (size_t)HALF * g.ldb * 2;
;     const size_t tstepA = 2 * hstepA, tstepB = 2 * hstepB;
;     const unsigned ldsw = (unsigned)wid * 1024u;
;     const int aoff = lds_byte(wr * 64 + fr, fq * 8), boff = lds_byte(wc * 32 + fr, fq * 8);
;     ...
;     Unit cur, nxt; int ui = 0;
;     if (!S.next(0, cur)) return;
;     f32x4 acc[2][2][4][2];
; #pragma unroll
;     for (int a = 0; a < 2; ++a)
; #pragma unroll
;         for (int b = 0; b < 2; ++b)
; #pragma unroll
;             for (int m = 0; m < 4; ++m)
; #pragma unroll
;                 for (int n = 0; n < 2; ++n) acc[a][b][m][n] = (f32x4){0.f, 0.f, 0.f, 0.f};
;     bf16x8 At[4][2], B0[2][2], B1[2][2];
;     const char* cA = (const char*)g.A + (size_t)cur.pm * tstepA; const char* cB = (const char*)g.Bt + (size_t)cur.pn * tstepB;
;     S.a_ready(cur);
;     if constexpr (SP2) {
;         PG8_STAGE(PG8_SB(0, 0), cB, voffB); PG8_STAGE(PG8_SB(0, 1), cB + hstepB, voffB); PG8_STAGE(PG8_SA(0, 0), cA, voffA); PG8_STAGE(PG8_SA(0, 1), cA + hstepA, voffA);
;         if (wr == 1) PG8_BAR;
;         PG8_WAIT_V(2); PG8_BAR;
;         PG8_STAGE(PG8_SB(1, 0), cB + kstep, voffB); PG8_STAGE(PG8_SA(1, 0), cA + kstep, voffA); PG8_STAGE(PG8_SB(1, 1), cB + hstepB + kstep, voffB);
;         PG8_WAIT_V(6); PG8_BAR;
.LBB0_1853:
	s_load_dwordx2 s[8:9], s[82:83], 0xb8
	v_mov_b32_e32 v0, v1
	s_waitcnt lgkmcnt(0)
	v_readlane_b32 s0, v253, 21
	v_mbcnt_lo_u32_b32 v0, -1, v0
	v_mbcnt_hi_u32_b32 v0, -1, v0
	v_or_b32_e32 v0, s0, v0
	s_and_b64 vcc, exec, s[38:39]
	v_readfirstlane_b32 s0, v0
	v_mov_b32_e32 v0, v1
	s_andn2_b32 s0, s0, 63
	v_mbcnt_lo_u32_b32 v0, -1, v0
	v_mbcnt_hi_u32_b32 v0, -1, v0
	v_or_b32_e32 v18, s0, v0
	s_nop 0
	v_readfirstlane_b32 s10, v18
	s_cbranch_vccnz .LBB0_1877
	v_lshlrev_b32_e32 v0, 4, v18
	v_add_u32_e32 v2, 0x2000, v0
	v_ashrrev_i32_e32 v3, 31, v2
	v_lshrrev_b32_e32 v3, 22, v3
	v_add_u32_e32 v3, v2, v3
	v_ashrrev_i32_e32 v10, 10, v3
	v_mul_i32_i24_e32 v3, 0x400, v10
	v_sub_u32_e32 v2, v2, v3
	v_lshrrev_b32_e32 v3, 4, v2
	v_bitop3_b32 v2, v3, v2, 32 bitop3:0x6c
	v_ashrrev_i32_e32 v3, 31, v2
	v_lshrrev_b32_e32 v3, 26, v3
	v_add_u32_e32 v3, v2, v3
	v_ashrrev_i32_e32 v11, 6, v3
	v_lshlrev_b32_e32 v5, 5, v10
	v_and_b32_e32 v3, 0xc0, v3
	v_and_b32_e32 v12, 32, v5
	v_sub_u32_e32 v2, v2, v3
	v_mov_b32_e32 v5, 1
	v_ashrrev_i16_sdwa v2, v5, sext(v2) dst_sel:DWORD dst_unused:UNUSED_PAD src0_sel:DWORD src1_sel:BYTE_0
	v_bfe_i32 v13, v2, 0, 16
	v_bfe_i32 v2, v18, 27, 1
	v_lshrrev_b32_e32 v2, 22, v2
	v_add_u32_e32 v2, v0, v2
	v_and_b32_e32 v2, 0xfffffc00, v2
	v_sub_u32_e32 v0, v0, v2
	s_add_u32 s2, s8, 0x22d90000
	v_lshrrev_b32_e32 v2, 4, v0
	v_ashrrev_i32_e32 v3, 31, v18
	s_addc_u32 s22, s9, 0
	s_mul_i32 s0, s78, 0x2c00000
	v_bitop3_b32 v0, v2, v0, 32 bitop3:0x6c
	v_lshrrev_b32_e32 v3, 26, v3
	s_add_u32 s0, s8, s0
	v_lshlrev_b32_e32 v4, 3, v10
	v_ashrrev_i32_e32 v2, 31, v0
	v_add_u32_e32 v3, v18, v3
	s_addc_u32 s1, s9, 0
	v_and_b32_e32 v4, 0x7ffff0, v4
	v_lshrrev_b32_e32 v2, 26, v2
	v_ashrrev_i32_e32 v15, 6, v3
	s_add_u32 s24, s0, 0xc790000
	v_add_u32_e32 v4, v11, v4
	s_movk_i32 s0, 0x1600
	v_add_u32_e32 v2, v0, v2
	v_lshlrev_b32_e32 v3, 3, v15
	v_lshl_or_b32 v228, v4, 6, v12
	v_add_lshl_u32 v228, v228, v13, 1
	v_mov_b32_e32 v229, 0
	v_mul_lo_u32 v4, v4, s0
	v_ashrrev_i32_e32 v14, 6, v2
	v_and_b32_e32 v3, 0x7ffff0, v3
	s_addc_u32 s25, s1, 0
	s_ashr_i32 s11, s10, 6
	v_or_b32_e32 v4, v4, v12
	v_add_u32_e32 v3, v14, v3
	v_and_b32_e32 v2, 0xc0, v2
	s_ashr_i32 s12, s10, 8
	s_lshl_b32 s40, s11, 10
	s_waitcnt vmcnt(0)
	v_add_lshl_u32 v130, v4, v13, 1
	v_mov_b32_e32 v226, v3
	v_mul_lo_u32 v3, v3, s0
	v_lshlrev_b32_e32 v4, 5, v15
	v_sub_u32_e32 v0, v0, v2
	v_readlane_b32 s0, v255, 22
	v_and_b32_e32 v16, 32, v4
	v_ashrrev_i16_sdwa v0, v5, sext(v0) dst_sel:DWORD dst_unused:UNUSED_PAD src0_sel:DWORD src1_sel:BYTE_0
	s_add_u32 s16, s24, s0
	v_readlane_b32 s0, v255, 20
	v_or_b32_e32 v3, v3, v16
	v_bfe_i32 v17, v0, 0, 16
	s_addc_u32 s17, s25, s0
	s_add_i32 s33, s40, 0
	v_add_lshl_u32 v0, v3, v17, 1
	v_lshl_or_b32 v226, v226, 6, v16
	v_add_lshl_u32 v226, v226, v17, 1
	v_mov_b32_e32 v227, 0
	s_add_i32 m0, s33, 0x10000
	v_mov_b32_e32 v131, v1
	global_load_lds_dwordx4 v0, s[16:17]
	s_add_i32 m0, s33, 0x12000
	s_add_u32 s0, s16, 0x160000
	global_load_lds_dwordx4 v130, s[16:17]
	s_addc_u32 s1, s17, 0
	s_add_i32 m0, s33, 0x14000
	v_lshl_add_u64 v[8:9], s[16:17], 0, v[0:1]
	global_load_lds_dwordx4 v0, s[0:1]
	s_add_i32 m0, s33, 0x16000
	v_lshl_add_u64 v[6:7], s[16:17], 0, v[130:131]
	global_load_lds_dwordx4 v130, s[0:1]
	v_readlane_b32 s0, v255, 19
	s_add_u32 s14, s2, s0
	v_readlane_b32 s0, v255, 16
	s_addc_u32 s15, s22, s0
	s_add_i32 s41, s33, 0x2000
	s_mov_b32 m0, s33
	s_add_u32 s0, s14, 0x4000
	global_load_lds_dwordx4 v226, s[14:15]
	s_mov_b32 m0, s41
	s_addc_u32 s1, s15, 0
	s_add_i32 s42, s33, 0x4000
	global_load_lds_dwordx4 v228, s[14:15]
	s_mov_b32 m0, s42
	s_add_i32 s43, s33, 0x6000
	global_load_lds_dwordx4 v226, s[0:1]
	s_mov_b32 m0, s43
	s_cmp_eq_u32 s12, 1
	global_load_lds_dwordx4 v228, s[0:1]
	v_lshl_add_u64 v[2:3], s[14:15], 0, v[226:227]
	s_cselect_b64 s[0:1], -1, 0
	s_cmp_lg_u32 s12, 1
	v_lshl_add_u64 v[4:5], s[14:15], 0, v[228:229]
	s_cbranch_scc1 .LBB0_1856
	s_barrier
.LBB0_1856:
	s_add_u32 s6, s8, 0x16d90000
	s_addc_u32 s7, s9, 0
	s_mul_i32 s13, s78, 0x48000
	s_add_u32 s8, s8, s13
	s_addc_u32 s9, s9, 0
	v_bfe_u32 v19, v18, 4, 2
	s_add_u32 s44, s8, 0x110000
	v_and_b32_e32 v20, 15, v18
	v_lshlrev_b32_e32 v21, 4, v19
	v_lshlrev_b32_e32 v18, 2, v18
	s_addc_u32 s45, s9, 0
	v_lshl_or_b32 v158, s12, 6, v20
	v_lshl_or_b32 v20, v20, 6, v21
	s_lshl_b32 s8, s12, 13
	v_and_b32_e32 v18, 32, v18
	v_bitop3_b32 v21, v20, s8, v18 bitop3:0xde
	s_lshl_b32 s8, s11, 5
	s_and_b32 s11, s8, 0x60
	s_add_i32 m0, s33, 0x18000
	v_lshl_add_u64 v[8:9], v[8:9], 0, s[30:31]
	s_lshl_b32 s8, s11, 7
	s_waitcnt vmcnt(2)
	s_barrier
	global_load_lds_dwordx4 v[8:9], off
	v_lshl_add_u64 v[6:7], v[6:7], 0, s[30:31]
	s_add_i32 m0, s33, 0x1a000
	s_add_i32 s46, s33, 0x8000
	s_add_i32 s47, s33, 0xa000
	v_bitop3_b32 v159, v20, s8, v18 bitop3:0xde
	global_load_lds_dwordx4 v[6:7], off
	s_mov_b64 s[100:101], 0x8000
	v_lshl_add_u64 v[2:3], v[2:3], 0, s[100:101]
	s_mov_b32 m0, s46
	s_add_u32 s8, s16, 0x160080
	global_load_lds_dwordx4 v[2:3], off
	v_lshl_add_u64 v[2:3], v[4:5], 0, s[100:101]
	s_mov_b32 m0, s47
	s_addc_u32 s9, s17, 0
	global_load_lds_dwordx4 v[2:3], off
	s_add_i32 m0, s33, 0x1c000
	v_lshl_add_u64 v[2:3], s[8:9], 0, v[0:1]
	global_load_lds_dwordx4 v[2:3], off
	v_lshl_add_u64 v[2:3], s[8:9], 0, v[130:131]
	s_add_i32 m0, s33, 0x1e000
	s_movk_i32 s13, 0x1600
	global_load_lds_dwordx4 v[2:3], off
	v_lshrrev_b32_e32 v3, 1, v10
	v_mul_lo_u32 v2, v11, s13
	s_mov_b32 s12, 0x16000
	s_cmpk_lt_u32 s10, 0x100
	v_lshl_or_b32 v160, v19, 2, s11
	v_mad_u64_u32 v[2:3], s[10:11], v3, s12, v[2:3]
	v_or_b32_e32 v2, v2, v12
	v_add_lshl_u32 v2, v2, v13, 1
	v_mov_b32_e32 v3, v1
	s_mov_b64 s[18:19], 0x160080
	s_mov_b64 s[100:101], 0xc000
	v_lshl_add_u64 v[132:133], v[228:229], 0, s[100:101]
	v_lshrrev_b32_e32 v3, 1, v15
	v_mul_lo_u32 v2, v14, s13
	v_mad_u64_u32 v[2:3], s[10:11], v3, s12, v[2:3]
	s_waitcnt vmcnt(6)
	v_or_b32_e32 v2, v2, v16
	v_add_lshl_u32 v2, v2, v17, 1
	v_mov_b32_e32 v3, v1
	v_readlane_b32 s10, v255, 17
	s_cselect_b64 s[8:9], -1, 0
	v_lshl_add_u64 v[134:135], v[226:227], 0, s[100:101]
	s_mov_b32 s48, 0
	v_add_u32_e32 v161, 0, v21
	v_readlane_b32 s26, v255, 21
	s_mov_b32 s51, s10
	s_barrier
	v_readlane_b32 s11, v255, 18
	s_branch .LBB0_1859

; #define PG8_STAGE(bufoff, gbase, voff) do { _Pragma("unroll") for (int _i = 0; _i < 2; ++_i) \
;         __builtin_amdgcn_global_load_lds((const unsigned*)((const char*)(gbase) + (voff)[_i]), (PG8_LAS unsigned*)(lds + (bufoff) + ldsw + _i * 8192), 16, 0, 0); } while (0)
; #define PG8_LDA(dst, b, h) do { _Pragma("unroll") for (int m = 0; m < 4; ++m) _Pragma("unroll") for (int k = 0; k < 2; ++k) dst[m][k] = *(const PG8_LAS bf16x8*)(lds + PG8_SA(b, h) + aoff + m * 2048 + k * 1024); } while (0)
; #define PG8_LDB(dst, b, h) do { _Pragma("unroll") for (int n = 0; n < 2; ++n) _Pragma("unroll") for (int k = 0; k < 2; ++k) dst[n][k] = *(const PG8_LAS bf16x8*)(lds + PG8_SB(b, h) + boff + n * 2048 + k * 1024); } while (0)
; #define PG8_MMA(ai, bj, At, Bt) do { __builtin_amdgcn_s_setprio(1); _Pragma("unroll") for (int m = 0; m < 4; ++m) _Pragma("unroll") for (int n = 0; n < 2; ++n) _Pragma("unroll") for (int k = 0; k < 2; ++k) \
;         acc[ai][bj][m][n] = __builtin_amdgcn_mfma_f32_16x16x32_bf16(Bt[n][k], At[m][k], acc[ai][bj][m][n], 0, 0, 0); __builtin_amdgcn_s_setprio(0); } while (0)
; template <class Epi, class Sched, bool ALIGN_EPI = false, bool SP2 = false>
; __device__ __forceinline__ void gemm_phase(PG8_LAS unsigned char* lds, const Gemm g, const Sched& S, const Epi& E, int wave_s) {
;     ...
;         for (int t = 0; t < nt; t += 2) {
;             const bool last = (t == nt - 2);
;             const char* a1 = cA + (size_t)(t + 1) * kstep;
;             const char* a2 = last ? nA : cA + (size_t)(t + 2) * kstep; const char* b2 = last ? nB : cB + (size_t)(t + 2) * kstep;
;             const char* a3 = a2 + kstep; const char* b3 = b2 + kstep;
;             if (last && has_next) S.a_ready(nxt);
;             if constexpr (Epi::HAS_MID) { if (t == nt / 2) E.mid(acc, cur, wr, wc, fr, fq); }
;             if constexpr (SP2) {
;             PG8_LDB(B0, 0, 0); PG8_LDB(B1, 0, 1); PG8_SCHED; PG8_LDA(At, 0, 0); PG8_STAGE(PG8_SA(1, 1), a1 + hstepA, voffA);
;             PG8_WAIT_V(8); PG8_WAIT_L(0); PG8_BAR; PG8_MMA(0, 0, At, B0); PG8_MMA(0, 1, At, B1); PG8_BAR; PG8_SCHED;
;             PG8_LDA(At, 0, 1); PG8_STAGE(PG8_SB(0, 0), b2, voffB); PG8_STAGE(PG8_SB(0, 1), b2 + hstepB, voffB); PG8_STAGE(PG8_SA(0, 0), a2, voffA);
;             PG8_WAIT_V(8); PG8_WAIT_L(0); PG8_BAR; PG8_MMA(1, 0, At, B0); PG8_MMA(1, 1, At, B1); PG8_BAR; PG8_SCHED;
.LBB0_1870:
	s_add_u32 s16, s14, 0x10000
	s_addc_u32 s17, s15, 0
	s_add_i32 s34, 0, 0x10000
	s_cmpk_eq_i32 s39, 0x54
	s_cselect_b32 s21, s11, s17
	s_cselect_b32 s20, s10, s16
	s_cselect_b32 s19, s13, s38
	s_cselect_b32 s18, s12, s27
	s_add_i32 s35, 0, 0x14000
	v_add_u32_e32 v148, s34, v159
	v_add_u32_e32 v156, s35, v159
	ds_read_b128 v[136:139], v148
	ds_read_b128 v[140:143], v148 offset:1024
	ds_read_b128 v[144:147], v148 offset:2048
	ds_read_b128 v[148:151], v148 offset:3072
	ds_read_b128 v[152:155], v156
	ds_read_b128 v[162:165], v156 offset:1024
	ds_read_b128 v[166:169], v156 offset:2048
	ds_read_b128 v[176:179], v156 offset:3072
	v_lshl_add_u64 v[156:157], s[14:15], 0, v[134:135]
	s_add_i32 m0, s33, 0xc000
	ds_read_b128 v[180:183], v161
	ds_read_b128 v[184:187], v161 offset:1024
	ds_read_b128 v[188:191], v161 offset:2048
	ds_read_b128 v[192:195], v161 offset:3072
	ds_read_b128 v[196:199], v161 offset:4096
	ds_read_b128 v[208:211], v161 offset:5120
	ds_read_b128 v[212:215], v161 offset:6144
	ds_read_b128 v[216:219], v161 offset:7168
	global_load_lds_dwordx4 v[156:157], off
	v_lshl_add_u64 v[156:157], s[14:15], 0, v[132:133]
	s_add_i32 m0, s33, 0xe000
	s_nop 0
	global_load_lds_dwordx4 v[156:157], off
	s_waitcnt vmcnt(8)
	s_waitcnt lgkmcnt(0)
	s_barrier
	s_setprio 1
	s_waitcnt lgkmcnt(0)
	v_mfma_f32_16x16x32_bf16 v[126:129], v[180:183], v[136:139], v[126:129]
	v_mfma_f32_16x16x32_bf16 v[122:125], v[180:183], v[144:147], v[122:125]
	v_mfma_f32_16x16x32_bf16 v[110:113], v[188:191], v[136:139], v[110:113]
	v_mfma_f32_16x16x32_bf16 v[106:109], v[188:191], v[144:147], v[106:109]
	v_mfma_f32_16x16x32_bf16 v[94:97], v[196:199], v[136:139], v[94:97]
	v_mfma_f32_16x16x32_bf16 v[90:93], v[196:199], v[144:147], v[90:93]
	v_mfma_f32_16x16x32_bf16 v[78:81], v[212:215], v[136:139], v[78:81]
	v_mfma_f32_16x16x32_bf16 v[74:77], v[212:215], v[144:147], v[74:77]
	v_mfma_f32_16x16x32_bf16 v[126:129], v[184:187], v[140:143], v[126:129]
	v_mfma_f32_16x16x32_bf16 v[122:125], v[184:187], v[148:151], v[122:125]
	v_mfma_f32_16x16x32_bf16 v[110:113], v[192:195], v[140:143], v[110:113]
	v_mfma_f32_16x16x32_bf16 v[106:109], v[192:195], v[148:151], v[106:109]
	v_mfma_f32_16x16x32_bf16 v[94:97], v[208:211], v[140:143], v[94:97]
	v_mfma_f32_16x16x32_bf16 v[90:93], v[208:211], v[148:151], v[90:93]
	v_mfma_f32_16x16x32_bf16 v[78:81], v[216:219], v[140:143], v[78:81]
	v_mfma_f32_16x16x32_bf16 v[74:77], v[216:219], v[148:151], v[74:77]
	s_setprio 0
	s_setprio 1
	v_mfma_f32_16x16x32_bf16 v[118:121], v[180:183], v[152:155], v[118:121]
	v_mfma_f32_16x16x32_bf16 v[114:117], v[180:183], v[166:169], v[114:117]
	v_mfma_f32_16x16x32_bf16 v[102:105], v[188:191], v[152:155], v[102:105]
	v_mfma_f32_16x16x32_bf16 v[98:101], v[188:191], v[166:169], v[98:101]
	v_mfma_f32_16x16x32_bf16 v[86:89], v[196:199], v[152:155], v[86:89]
	v_mfma_f32_16x16x32_bf16 v[82:85], v[196:199], v[166:169], v[82:85]
	v_mfma_f32_16x16x32_bf16 v[70:73], v[212:215], v[152:155], v[70:73]
	v_mfma_f32_16x16x32_bf16 v[66:69], v[212:215], v[166:169], v[66:69]
	v_mfma_f32_16x16x32_bf16 v[118:121], v[184:187], v[162:165], v[118:121]
	v_mfma_f32_16x16x32_bf16 v[114:117], v[184:187], v[176:179], v[114:117]
	v_mfma_f32_16x16x32_bf16 v[102:105], v[192:195], v[162:165], v[102:105]
	v_mfma_f32_16x16x32_bf16 v[98:101], v[192:195], v[176:179], v[98:101]
	v_mfma_f32_16x16x32_bf16 v[86:89], v[208:211], v[162:165], v[86:89]
	v_mfma_f32_16x16x32_bf16 v[82:85], v[208:211], v[176:179], v[82:85]
	v_mfma_f32_16x16x32_bf16 v[70:73], v[216:219], v[162:165], v[70:73]
	v_mfma_f32_16x16x32_bf16 v[66:69], v[216:219], v[176:179], v[66:69]
	s_setprio 0
	s_barrier
	s_add_i32 s14, s34, s40
	v_lshl_add_u64 v[156:157], s[18:19], 0, v[0:1]
	s_mov_b32 m0, s14
	ds_read_b128 v[180:183], v161 offset:16384
	ds_read_b128 v[184:187], v161 offset:17408
	ds_read_b128 v[188:191], v161 offset:18432
	ds_read_b128 v[192:195], v161 offset:19456
	ds_read_b128 v[196:199], v161 offset:20480
	ds_read_b128 v[208:211], v161 offset:21504
	ds_read_b128 v[212:215], v161 offset:22528
	ds_read_b128 v[216:219], v161 offset:23552
	global_load_lds_dwordx4 v[156:157], off
	s_add_i32 m0, s14, 0x2000
	s_add_u32 s14, s18, 0x160000
	v_lshl_add_u64 v[170:171], s[18:19], 0, v[130:131]
	s_addc_u32 s15, s19, 0
	s_add_i32 s34, s35, s40
	global_load_lds_dwordx4 v[170:171], off
	v_lshl_add_u64 v[200:201], s[14:15], 0, v[0:1]
	s_mov_b32 m0, s34
	v_lshl_add_u64 v[220:221], s[20:21], 0, v[228:229]
	global_load_lds_dwordx4 v[200:201], off
	v_lshl_add_u64 v[200:201], s[14:15], 0, v[130:131]
	s_add_i32 m0, s34, 0x2000
	s_nop 0
	global_load_lds_dwordx4 v[200:201], off
	v_lshl_add_u64 v[200:201], s[20:21], 0, v[226:227]
	s_mov_b32 m0, s33
	s_nop 0
	global_load_lds_dwordx4 v[200:201], off
	s_mov_b32 m0, s41
	s_nop 0
	global_load_lds_dwordx4 v[220:221], off
	s_waitcnt vmcnt(8)
	s_waitcnt lgkmcnt(0)
	s_barrier
; #define PG8_STAGE(bufoff, gbase, voff) do { _Pragma("unroll") for (int _i = 0; _i < 2; ++_i) \
;         __builtin_amdgcn_global_load_lds((const unsigned*)((const char*)(gbase) + (voff)[_i]), (PG8_LAS unsigned*)(lds + (bufoff) + ldsw + _i * 8192), 16, 0, 0); } while (0)
; #define PG8_LDA(dst, b, h) do { _Pragma("unroll") for (int m = 0; m < 4; ++m) _Pragma("unroll") for (int k = 0; k < 2; ++k) dst[m][k] = *(const PG8_LAS bf16x8*)(lds + PG8_SA(b, h) + aoff + m * 2048 + k * 1024); } while (0)
; #define PG8_LDB(dst, b, h) do { _Pragma("unroll") for (int n = 0; n < 2; ++n) _Pragma("unroll") for (int k = 0; k < 2; ++k) dst[n][k] = *(const PG8_LAS bf16x8*)(lds + PG8_SB(b, h) + boff + n * 2048 + k * 1024); } while (0)
; #define PG8_MMA(ai, bj, At, Bt) do { __builtin_amdgcn_s_setprio(1); _Pragma("unroll") for (int m = 0; m < 4; ++m) _Pragma("unroll") for (int n = 0; n < 2; ++n) _Pragma("unroll") for (int k = 0; k < 2; ++k) \
;         acc[ai][bj][m][n] = __builtin_amdgcn_mfma_f32_16x16x32_bf16(Bt[n][k], At[m][k], acc[ai][bj][m][n], 0, 0, 0); __builtin_amdgcn_s_setprio(0); } while (0)
; #define PG8_WAIT_V(n) asm volatile("s_waitcnt vmcnt(" #n ")" ::: "memory")
; #define PG8_WAIT_L(n) asm volatile("s_waitcnt lgkmcnt(" #n ")" ::: "memory")
; #define PG8_BAR __builtin_amdgcn_s_barrier()
; #define PG8_SCHED __builtin_amdgcn_sched_barrier(0)
; template <class Epi, class Sched, bool ALIGN_EPI = false, bool SP2 = false>
; __device__ __forceinline__ void gemm_phase(PG8_LAS unsigned char* lds, const Gemm g, const Sched& S, const Epi& E, int wave_s) {
;     ...
;             PG8_LDA(At, 0, 1); PG8_STAGE(PG8_SB(0, 0), b2, voffB); PG8_STAGE(PG8_SB(0, 1), b2 + hstepB, voffB); PG8_STAGE(PG8_SA(0, 0), a2, voffA);
;             PG8_WAIT_V(8); PG8_WAIT_L(0); PG8_BAR; PG8_MMA(1, 0, At, B0); PG8_MMA(1, 1, At, B1); PG8_BAR; PG8_SCHED;
;             PG8_LDB(B0, 1, 0); PG8_LDB(B1, 1, 1); PG8_SCHED; PG8_LDA(At, 1, 0); PG8_STAGE(PG8_SA(0, 1), a2 + hstepA, voffA);
;             PG8_WAIT_V(8); PG8_WAIT_L(0); PG8_BAR; PG8_MMA(0, 0, At, B0); PG8_MMA(0, 1, At, B1); PG8_BAR; PG8_SCHED;
;             PG8_LDA(At, 1, 1); PG8_STAGE(PG8_SB(1, 0), b3, voffB); PG8_STAGE(PG8_SB(1, 1), b3 + hstepB, voffB); PG8_STAGE(PG8_SA(1, 0), a3, voffA);
	s_setprio 1
	s_waitcnt lgkmcnt(0)
	v_mfma_f32_16x16x32_bf16 v[62:65], v[180:183], v[136:139], v[62:65]
	v_mfma_f32_16x16x32_bf16 v[58:61], v[180:183], v[144:147], v[58:61]
	v_mfma_f32_16x16x32_bf16 v[46:49], v[188:191], v[136:139], v[46:49]
	v_mfma_f32_16x16x32_bf16 v[42:45], v[188:191], v[144:147], v[42:45]
	v_mfma_f32_16x16x32_bf16 v[30:33], v[196:199], v[136:139], v[30:33]
	v_mfma_f32_16x16x32_bf16 v[26:29], v[196:199], v[144:147], v[26:29]
	v_mfma_f32_16x16x32_bf16 v[14:17], v[212:215], v[136:139], v[14:17]
	v_mfma_f32_16x16x32_bf16 v[10:13], v[212:215], v[144:147], v[10:13]
	v_mfma_f32_16x16x32_bf16 v[62:65], v[184:187], v[140:143], v[62:65]
	v_mfma_f32_16x16x32_bf16 v[58:61], v[184:187], v[148:151], v[58:61]
	v_mfma_f32_16x16x32_bf16 v[46:49], v[192:195], v[140:143], v[46:49]
	v_mfma_f32_16x16x32_bf16 v[42:45], v[192:195], v[148:151], v[42:45]
	v_mfma_f32_16x16x32_bf16 v[30:33], v[208:211], v[140:143], v[30:33]
	v_mfma_f32_16x16x32_bf16 v[26:29], v[208:211], v[148:151], v[26:29]
	v_mfma_f32_16x16x32_bf16 v[14:17], v[216:219], v[140:143], v[14:17]
	v_mfma_f32_16x16x32_bf16 v[10:13], v[216:219], v[148:151], v[10:13]
	s_setprio 0
	s_setprio 1
	v_mfma_f32_16x16x32_bf16 v[54:57], v[180:183], v[152:155], v[54:57]
	v_mfma_f32_16x16x32_bf16 v[50:53], v[180:183], v[166:169], v[50:53]
	v_mfma_f32_16x16x32_bf16 v[38:41], v[188:191], v[152:155], v[38:41]
	v_mfma_f32_16x16x32_bf16 v[34:37], v[188:191], v[166:169], v[34:37]
	v_mfma_f32_16x16x32_bf16 v[22:25], v[196:199], v[152:155], v[22:25]
	v_mfma_f32_16x16x32_bf16 v[18:21], v[196:199], v[166:169], v[18:21]
	v_mfma_f32_16x16x32_bf16 v[6:9], v[212:215], v[152:155], v[6:9]
	v_mfma_f32_16x16x32_bf16 v[2:5], v[212:215], v[166:169], v[2:5]
	v_mfma_f32_16x16x32_bf16 v[54:57], v[184:187], v[162:165], v[54:57]
	v_mfma_f32_16x16x32_bf16 v[50:53], v[184:187], v[176:179], v[50:53]
	v_mfma_f32_16x16x32_bf16 v[38:41], v[192:195], v[162:165], v[38:41]
	v_mfma_f32_16x16x32_bf16 v[34:37], v[192:195], v[176:179], v[34:37]
	v_mfma_f32_16x16x32_bf16 v[22:25], v[208:211], v[162:165], v[22:25]
	v_mfma_f32_16x16x32_bf16 v[18:21], v[208:211], v[176:179], v[18:21]
	v_mfma_f32_16x16x32_bf16 v[6:9], v[216:219], v[162:165], v[6:9]
	v_mfma_f32_16x16x32_bf16 v[2:5], v[216:219], v[176:179], v[2:5]
	s_setprio 0
	s_barrier
	s_add_i32 s34, 0, 0x18000
	s_add_i32 s35, 0, 0x1c000
	v_add_u32_e32 v148, s34, v159
	v_add_u32_e32 v176, s35, v159
	ds_read_b128 v[136:139], v148
	ds_read_b128 v[140:143], v148 offset:1024
	ds_read_b128 v[144:147], v148 offset:2048
	ds_read_b128 v[148:151], v148 offset:3072
	ds_read_b128 v[152:155], v176
	ds_read_b128 v[162:165], v176 offset:1024
	ds_read_b128 v[166:169], v176 offset:2048
	ds_read_b128 v[176:179], v176 offset:3072
	s_add_u32 s14, s20, 0x4000
	s_addc_u32 s15, s21, 0
	s_mov_b32 m0, s42
	v_lshl_add_u64 v[222:223], s[14:15], 0, v[226:227]
	ds_read_b128 v[180:183], v161 offset:32768
	ds_read_b128 v[184:187], v161 offset:33792
	ds_read_b128 v[188:191], v161 offset:34816
	ds_read_b128 v[192:195], v161 offset:35840
	ds_read_b128 v[196:199], v161 offset:36864
	ds_read_b128 v[208:211], v161 offset:37888
	ds_read_b128 v[212:215], v161 offset:38912
	ds_read_b128 v[216:219], v161 offset:39936
	global_load_lds_dwordx4 v[222:223], off
	v_lshl_add_u64 v[222:223], s[14:15], 0, v[228:229]
	s_mov_b32 m0, s43
	s_nop 0
	global_load_lds_dwordx4 v[222:223], off
	s_waitcnt vmcnt(8)
	s_waitcnt lgkmcnt(0)
	s_barrier
	s_setprio 1
	s_waitcnt lgkmcnt(0)
	v_mfma_f32_16x16x32_bf16 v[126:129], v[180:183], v[136:139], v[126:129]
	v_mfma_f32_16x16x32_bf16 v[122:125], v[180:183], v[144:147], v[122:125]
	v_mfma_f32_16x16x32_bf16 v[110:113], v[188:191], v[136:139], v[110:113]
	v_mfma_f32_16x16x32_bf16 v[106:109], v[188:191], v[144:147], v[106:109]
	v_mfma_f32_16x16x32_bf16 v[94:97], v[196:199], v[136:139], v[94:97]
	v_mfma_f32_16x16x32_bf16 v[90:93], v[196:199], v[144:147], v[90:93]
	v_mfma_f32_16x16x32_bf16 v[78:81], v[212:215], v[136:139], v[78:81]
	v_mfma_f32_16x16x32_bf16 v[74:77], v[212:215], v[144:147], v[74:77]
	v_mfma_f32_16x16x32_bf16 v[126:129], v[184:187], v[140:143], v[126:129]
	v_mfma_f32_16x16x32_bf16 v[122:125], v[184:187], v[148:151], v[122:125]
	v_mfma_f32_16x16x32_bf16 v[110:113], v[192:195], v[140:143], v[110:113]
	v_mfma_f32_16x16x32_bf16 v[106:109], v[192:195], v[148:151], v[106:109]
	v_mfma_f32_16x16x32_bf16 v[94:97], v[208:211], v[140:143], v[94:97]
	v_mfma_f32_16x16x32_bf16 v[90:93], v[208:211], v[148:151], v[90:93]
	v_mfma_f32_16x16x32_bf16 v[78:81], v[216:219], v[140:143], v[78:81]
	v_mfma_f32_16x16x32_bf16 v[74:77], v[216:219], v[148:151], v[74:77]
	s_setprio 0
	s_setprio 1
	v_mfma_f32_16x16x32_bf16 v[118:121], v[180:183], v[152:155], v[118:121]
	v_mfma_f32_16x16x32_bf16 v[114:117], v[180:183], v[166:169], v[114:117]
	v_mfma_f32_16x16x32_bf16 v[102:105], v[188:191], v[152:155], v[102:105]
	v_mfma_f32_16x16x32_bf16 v[98:101], v[188:191], v[166:169], v[98:101]
	v_mfma_f32_16x16x32_bf16 v[86:89], v[196:199], v[152:155], v[86:89]
	v_mfma_f32_16x16x32_bf16 v[82:85], v[196:199], v[166:169], v[82:85]
	v_mfma_f32_16x16x32_bf16 v[70:73], v[212:215], v[152:155], v[70:73]
	v_mfma_f32_16x16x32_bf16 v[66:69], v[212:215], v[166:169], v[66:69]
	v_mfma_f32_16x16x32_bf16 v[118:121], v[184:187], v[162:165], v[118:121]
	v_mfma_f32_16x16x32_bf16 v[114:117], v[184:187], v[176:179], v[114:117]
	v_mfma_f32_16x16x32_bf16 v[102:105], v[192:195], v[162:165], v[102:105]
	v_mfma_f32_16x16x32_bf16 v[98:101], v[192:195], v[176:179], v[98:101]
	v_mfma_f32_16x16x32_bf16 v[86:89], v[208:211], v[162:165], v[86:89]
	v_mfma_f32_16x16x32_bf16 v[82:85], v[208:211], v[176:179], v[82:85]
	v_mfma_f32_16x16x32_bf16 v[70:73], v[216:219], v[162:165], v[70:73]
	v_mfma_f32_16x16x32_bf16 v[66:69], v[216:219], v[176:179], v[66:69]
	s_setprio 0
	s_barrier
; #define PG8_STAGE(bufoff, gbase, voff) do { _Pragma("unroll") for (int _i = 0; _i < 2; ++_i) \
;         __builtin_amdgcn_global_load_lds((const unsigned*)((const char*)(gbase) + (voff)[_i]), (PG8_LAS unsigned*)(lds + (bufoff) + ldsw + _i * 8192), 16, 0, 0); } while (0)
; #define PG8_LDA(dst, b, h) do { _Pragma("unroll") for (int m = 0; m < 4; ++m) _Pragma("unroll") for (int k = 0; k < 2; ++k) dst[m][k] = *(const PG8_LAS bf16x8*)(lds + PG8_SA(b, h) + aoff + m * 2048 + k * 1024); } while (0)
; #define PG8_MMA(ai, bj, At, Bt) do { __builtin_amdgcn_s_setprio(1); _Pragma("unroll") for (int m = 0; m < 4; ++m) _Pragma("unroll") for (int n = 0; n < 2; ++n) _Pragma("unroll") for (int k = 0; k < 2; ++k) \
;         acc[ai][bj][m][n] = __builtin_amdgcn_mfma_f32_16x16x32_bf16(Bt[n][k], At[m][k], acc[ai][bj][m][n], 0, 0, 0); __builtin_amdgcn_s_setprio(0); } while (0)
; #define PG8_WAIT_V(n) asm volatile("s_waitcnt vmcnt(" #n ")" ::: "memory")
; #define PG8_WAIT_L(n) asm volatile("s_waitcnt lgkmcnt(" #n ")" ::: "memory")
; #define PG8_BAR __builtin_amdgcn_s_barrier()
; #define PG8_SCHED __builtin_amdgcn_sched_barrier(0)
; template <class Epi, class Sched, bool ALIGN_EPI = false, bool SP2 = false>
; __device__ __forceinline__ void gemm_phase(PG8_LAS unsigned char* lds, const Gemm g, const Sched& S, const Epi& E, int wave_s) {
;     ...
;             PG8_LDA(At, 1, 1); PG8_STAGE(PG8_SB(1, 0), b3, voffB); PG8_STAGE(PG8_SB(1, 1), b3 + hstepB, voffB); PG8_STAGE(PG8_SA(1, 0), a3, voffA);
;             PG8_WAIT_V(8); PG8_WAIT_L(0); PG8_BAR; PG8_MMA(1, 0, At, B0); PG8_MMA(1, 1, At, B1); PG8_BAR; PG8_SCHED;
	s_add_i32 s14, s34, s40
	v_lshl_add_u64 v[156:157], v[156:157], 0, s[30:31]
	s_mov_b32 m0, s14
	ds_read_b128 v[180:183], v161 offset:49152
	ds_read_b128 v[184:187], v161 offset:50176
	ds_read_b128 v[188:191], v161 offset:51200
	ds_read_b128 v[192:195], v161 offset:52224
	ds_read_b128 v[196:199], v161 offset:53248
	ds_read_b128 v[208:211], v161 offset:54272
	ds_read_b128 v[212:215], v161 offset:55296
	ds_read_b128 v[216:219], v161 offset:56320
	global_load_lds_dwordx4 v[156:157], off
	s_add_i32 m0, s14, 0x2000
	s_add_u32 s14, s18, 0x160080
	v_lshl_add_u64 v[156:157], v[170:171], 0, s[30:31]
	s_addc_u32 s15, s19, 0
	s_add_i32 s18, s35, s40
	global_load_lds_dwordx4 v[156:157], off
	v_lshl_add_u64 v[156:157], s[14:15], 0, v[0:1]
	s_mov_b32 m0, s18
	s_nop 0
	global_load_lds_dwordx4 v[156:157], off
	v_lshl_add_u64 v[156:157], s[14:15], 0, v[130:131]
	s_add_i32 m0, s18, 0x2000
	s_nop 0
	global_load_lds_dwordx4 v[156:157], off
	s_mov_b64 s[100:101], 0x8000
	v_lshl_add_u64 v[156:157], v[200:201], 0, s[100:101]
	s_mov_b32 m0, s46
	s_nop 0
	global_load_lds_dwordx4 v[156:157], off
	v_lshl_add_u64 v[156:157], v[220:221], 0, s[100:101]
	s_mov_b32 m0, s47
	s_nop 0
	global_load_lds_dwordx4 v[156:157], off
	s_waitcnt vmcnt(8)
	s_waitcnt lgkmcnt(0)
	s_barrier
	s_setprio 1
	s_waitcnt lgkmcnt(0)
	v_mfma_f32_16x16x32_bf16 v[62:65], v[180:183], v[136:139], v[62:65]
	v_mfma_f32_16x16x32_bf16 v[58:61], v[180:183], v[144:147], v[58:61]
	v_mfma_f32_16x16x32_bf16 v[46:49], v[188:191], v[136:139], v[46:49]
	v_mfma_f32_16x16x32_bf16 v[42:45], v[188:191], v[144:147], v[42:45]
	v_mfma_f32_16x16x32_bf16 v[30:33], v[196:199], v[136:139], v[30:33]
	v_mfma_f32_16x16x32_bf16 v[26:29], v[196:199], v[144:147], v[26:29]
	v_mfma_f32_16x16x32_bf16 v[14:17], v[212:215], v[136:139], v[14:17]
	v_mfma_f32_16x16x32_bf16 v[10:13], v[212:215], v[144:147], v[10:13]
	v_mfma_f32_16x16x32_bf16 v[62:65], v[184:187], v[140:143], v[62:65]
	v_mfma_f32_16x16x32_bf16 v[58:61], v[184:187], v[148:151], v[58:61]
	v_mfma_f32_16x16x32_bf16 v[46:49], v[192:195], v[140:143], v[46:49]
	v_mfma_f32_16x16x32_bf16 v[42:45], v[192:195], v[148:151], v[42:45]
	v_mfma_f32_16x16x32_bf16 v[30:33], v[208:211], v[140:143], v[30:33]
	v_mfma_f32_16x16x32_bf16 v[26:29], v[208:211], v[148:151], v[26:29]
	v_mfma_f32_16x16x32_bf16 v[14:17], v[216:219], v[140:143], v[14:17]
	v_mfma_f32_16x16x32_bf16 v[10:13], v[216:219], v[148:151], v[10:13]
	s_setprio 0
	s_setprio 1
	v_mfma_f32_16x16x32_bf16 v[54:57], v[180:183], v[152:155], v[54:57]
	v_mfma_f32_16x16x32_bf16 v[50:53], v[180:183], v[166:169], v[50:53]
	v_mfma_f32_16x16x32_bf16 v[38:41], v[188:191], v[152:155], v[38:41]
	v_mfma_f32_16x16x32_bf16 v[34:37], v[188:191], v[166:169], v[34:37]
	v_mfma_f32_16x16x32_bf16 v[22:25], v[196:199], v[152:155], v[22:25]
	v_mfma_f32_16x16x32_bf16 v[18:21], v[196:199], v[166:169], v[18:21]
	v_mfma_f32_16x16x32_bf16 v[6:9], v[212:215], v[152:155], v[6:9]
	v_mfma_f32_16x16x32_bf16 v[2:5], v[212:215], v[166:169], v[2:5]
	v_mfma_f32_16x16x32_bf16 v[54:57], v[184:187], v[162:165], v[54:57]
	v_mfma_f32_16x16x32_bf16 v[50:53], v[184:187], v[176:179], v[50:53]
	v_mfma_f32_16x16x32_bf16 v[38:41], v[192:195], v[162:165], v[38:41]
	v_mfma_f32_16x16x32_bf16 v[34:37], v[192:195], v[176:179], v[34:37]
	v_mfma_f32_16x16x32_bf16 v[22:25], v[208:211], v[162:165], v[22:25]
	v_mfma_f32_16x16x32_bf16 v[18:21], v[208:211], v[176:179], v[18:21]
	v_mfma_f32_16x16x32_bf16 v[6:9], v[216:219], v[162:165], v[6:9]
	v_mfma_f32_16x16x32_bf16 v[2:5], v[216:219], v[176:179], v[2:5]
	s_setprio 0
	s_barrier
	s_add_i32 s39, s39, 2
	s_add_u32 s27, s27, 0x100
	s_addc_u32 s38, s38, 0
	s_cmpk_gt_u32 s39, 0x55
	s_mov_b64 s[14:15], s[16:17]
	s_cbranch_scc0 .LBB0_1870
	s_and_b64 vcc, exec, s[8:9]
	s_cbranch_vccz .LBB0_1873
	s_barrier
